# LayerNorm phases: butterfly all-reduce lane exchanges moved from ds_bpermute (LDS round trip per level) to DPP row ops and permlane16/32 swaps (same values, same additions)
# speedup vs baseline: 1.0504x; 1.0042x over previous
; DI float shx(float v, int m, int lane) { return __builtin_bit_cast(float, __builtin_amdgcn_ds_bpermute((lane ^ m) << 2, __builtin_bit_cast(int, v))); }
; template <int PR>
; DI void prep_rows(const int lane, const Params& p, int l, int which, int rbeg, int rend, int gw, int nw) {
;     ...
;                 const bf16_t* src = P_WSB(OFF_Z) + (size_t)r2 * 1024;
; #pragma unroll
;                 for (int i = 0; i < 4; i += 2) { const u32x4 zz = *(const u32x4*)(src + PCOL(i)); const u32x2 zl = {zz[0], zz[1]}, zh = {zz[2], zz[3]}; v[rr][i] = unpk4(zl); v[rr][i + 1] = unpk4(zh); }
;     ...
;             for (int rr = 0; rr < PR; ++rr) { float s = 0.f;
; #pragma unroll
;                 for (int i = 0; i < 4; ++i) s += v[rr][i][0] + v[rr][i][1] + v[rr][i][2] + v[rr][i][3];
;                 sm[rr] = s; }
; #pragma unroll
;             for (int o = 32; o >= 1; o >>= 1)
; #pragma unroll
;                 for (int rr = 0; rr < PR; ++rr) sm[rr] += shx(sm[rr], o, lane);
.LBB0_84:
	global_load_dwordx4 v[12:15], v[76:77], off offset:-3072
	global_load_dwordx4 v[8:11], v[76:77], off offset:-2048
	global_load_dwordx4 v[4:7], v[76:77], off offset:-1024
	global_load_dwordx4 v[0:3], v[76:77], off
	v_add_co_u32_e32 v16, vcc, 0xfffff000, v76
	v_mov_b64_e32 v[32:33], s[22:23]
	s_nop 0
	v_addc_co_u32_e32 v17, vcc, -1, v77, vcc
	global_load_dwordx4 v[18:21], v[16:17], off offset:-3072
	global_load_dwordx4 v[22:25], v[16:17], off offset:-2048
	global_load_dwordx4 v[26:29], v[16:17], off offset:-1024
	global_load_dwordx4 v[34:37], v[76:77], off offset:-4096
	s_movk_i32 s0, 0xd000
	v_add_u32_e32 v64, s12, v64
	v_lshl_add_u64 v[76:77], v[76:77], 0, s[18:19]
	s_waitcnt vmcnt(0)
	v_lshlrev_b32_e32 v31, 16, v12
	v_lshlrev_b32_e32 v30, 16, v14
	v_and_b32_e32 v39, 0xffff0000, v12
	v_and_b32_e32 v38, 0xffff0000, v14
	s_waitcnt vmcnt(6)
	v_lshlrev_b32_e32 v58, 16, v10
	v_and_b32_e32 v44, 0xffff0000, v10
	v_lshlrev_b32_e32 v60, 16, v11
	v_and_b32_e32 v108, 0xffff0000, v11
	s_waitcnt vmcnt(5)
	v_lshlrev_b32_e32 v11, 16, v4
	v_lshlrev_b32_e32 v10, 16, v6
	v_and_b32_e32 v63, 0xffff0000, v4
	v_and_b32_e32 v62, 0xffff0000, v6
	v_lshlrev_b32_e32 v41, 16, v13
	v_lshlrev_b32_e32 v40, 16, v15
	v_lshlrev_b32_e32 v59, 16, v8
	v_and_b32_e32 v45, 0xffff0000, v8
	v_lshlrev_b32_e32 v61, 16, v9
	v_and_b32_e32 v109, 0xffff0000, v9
	v_lshlrev_b32_e32 v79, 16, v5
	v_lshlrev_b32_e32 v78, 16, v7
	v_pk_add_f32 v[8:9], v[30:31], v[38:39]
	v_pk_add_f32 v[48:49], v[10:11], v[62:63]
	v_and_b32_e32 v43, 0xffff0000, v13
	v_and_b32_e32 v42, 0xffff0000, v15
	v_and_b32_e32 v81, 0xffff0000, v5
	v_and_b32_e32 v80, 0xffff0000, v7
	s_waitcnt vmcnt(4)
	v_lshlrev_b32_e32 v83, 16, v0
	v_lshlrev_b32_e32 v82, 16, v2
	v_and_b32_e32 v85, 0xffff0000, v0
	v_and_b32_e32 v84, 0xffff0000, v2
	v_lshlrev_b32_e32 v7, 16, v1
	v_lshlrev_b32_e32 v6, 16, v3
	v_and_b32_e32 v5, 0xffff0000, v1
	v_and_b32_e32 v4, 0xffff0000, v3
	v_pk_add_f32 v[46:47], v[58:59], v[44:45]
	s_waitcnt vmcnt(3)
	v_lshlrev_b32_e32 v87, 16, v18
	v_lshlrev_b32_e32 v86, 16, v20
	v_and_b32_e32 v89, 0xffff0000, v18
	v_and_b32_e32 v88, 0xffff0000, v20
	v_lshlrev_b32_e32 v90, 16, v21
	v_and_b32_e32 v106, 0xffff0000, v21
	s_waitcnt vmcnt(2)
	v_lshlrev_b32_e32 v1, 16, v22
	v_lshlrev_b32_e32 v0, 16, v24
	v_and_b32_e32 v3, 0xffff0000, v22
	v_and_b32_e32 v2, 0xffff0000, v24
	v_lshlrev_b32_e32 v15, 16, v23
	v_lshlrev_b32_e32 v14, 16, v25
	v_and_b32_e32 v13, 0xffff0000, v23
	v_and_b32_e32 v12, 0xffff0000, v25
	s_waitcnt vmcnt(1)
	v_lshlrev_b32_e32 v21, 16, v26
	v_lshlrev_b32_e32 v20, 16, v28
	v_and_b32_e32 v25, 0xffff0000, v26
	v_and_b32_e32 v24, 0xffff0000, v28
	v_pk_add_f32 v[8:9], v[8:9], v[40:41]
	v_pk_add_f32 v[22:23], v[48:49], v[78:79]
	v_pk_add_f32 v[50:51], v[82:83], v[84:85]
	v_lshlrev_b32_e32 v91, 16, v19
	v_and_b32_e32 v107, 0xffff0000, v19
	v_lshlrev_b32_e32 v113, 16, v27
	v_lshlrev_b32_e32 v112, 16, v29
	s_waitcnt vmcnt(0)
	v_lshlrev_b32_e32 v119, 16, v34
	v_and_b32_e32 v121, 0xffff0000, v34
	v_lshlrev_b32_e32 v93, 16, v35
	v_and_b32_e32 v17, 0xffff0000, v35
	v_pk_add_f32 v[18:19], v[46:47], v[60:61]
	v_pk_add_f32 v[34:35], v[86:87], v[88:89]
	v_pk_add_f32 v[46:47], v[20:21], v[24:25]
	v_pk_add_f32 v[8:9], v[8:9], v[42:43]
	v_pk_add_f32 v[22:23], v[22:23], v[80:81]
	v_and_b32_e32 v27, 0xffff0000, v27
	v_and_b32_e32 v26, 0xffff0000, v29
	v_lshlrev_b32_e32 v118, 16, v36
	v_and_b32_e32 v120, 0xffff0000, v36
	v_pk_add_f32 v[28:29], v[50:51], v[6:7]
	v_pk_add_f32 v[34:35], v[34:35], v[90:91]
	v_pk_add_f32 v[46:47], v[46:47], v[112:113]
	v_add_f32_e32 v9, 0, v9
	v_add_f32_e32 v23, 0, v23
	v_lshlrev_b32_e32 v92, 16, v37
	v_and_b32_e32 v16, 0xffff0000, v37
	v_pk_add_f32 v[36:37], v[0:1], v[2:3]
	v_pk_add_f32 v[48:49], v[118:119], v[120:121]
	v_pk_add_f32 v[18:19], v[18:19], v[108:109]
	v_pk_add_f32 v[28:29], v[28:29], v[4:5]
	v_pk_add_f32 v[34:35], v[34:35], v[106:107]
	v_pk_add_f32 v[46:47], v[46:47], v[26:27]
	v_add_f32_e32 v8, v8, v9
	v_add_f32_e32 v9, v22, v23
	v_pk_add_f32 v[36:37], v[36:37], v[14:15]
	v_pk_add_f32 v[48:49], v[48:49], v[92:93]
	v_add_f32_e32 v22, 0, v35
	v_add_f32_e32 v23, 0, v47
	v_add_f32_e32 v8, v19, v8
	v_add_f32_e32 v9, v29, v9
	v_pk_add_f32 v[36:37], v[36:37], v[12:13]
	v_pk_add_f32 v[48:49], v[48:49], v[16:17]
	v_add_f32_e32 v19, v34, v22
	v_add_f32_e32 v22, v46, v23
	v_add_f32_e32 v8, v18, v8
	v_add_f32_e32 v9, v28, v9
	v_add_f32_e32 v18, v37, v19
	v_add_f32_e32 v19, v49, v22
	v_mov_b32_e32 v240, v8
	v_mov_b32_e32 v22, v8
	s_nop 1
	v_permlane32_swap_b32_e32 v240, v22
	s_nop 1
	v_mov_b32_dpp v22, v240 quad_perm:[0,1,2,3] row_mask:0xc bank_mask:0xf
	v_mov_b32_e32 v240, v9
	v_mov_b32_e32 v23, v9
	s_nop 1
	v_permlane32_swap_b32_e32 v240, v23
	s_nop 1
	v_mov_b32_dpp v23, v240 quad_perm:[0,1,2,3] row_mask:0xc bank_mask:0xf
	v_add_f32_e32 v18, v36, v18
	v_add_f32_e32 v19, v48, v19
	v_mov_b32_e32 v240, v18
	v_mov_b32_e32 v28, v18
	s_nop 1
	v_permlane32_swap_b32_e32 v240, v28
	s_nop 1
	v_mov_b32_dpp v28, v240 quad_perm:[0,1,2,3] row_mask:0xc bank_mask:0xf
	v_mov_b32_e32 v240, v19
	v_mov_b32_e32 v29, v19
	s_nop 1
	v_permlane32_swap_b32_e32 v240, v29
	s_nop 1
	v_mov_b32_dpp v29, v240 quad_perm:[0,1,2,3] row_mask:0xc bank_mask:0xf
	s_waitcnt lgkmcnt(0)
	v_add_f32_e32 v8, v8, v22
	s_waitcnt lgkmcnt(2)
	v_add_f32_e32 v9, v9, v23
	v_mov_b32_e32 v240, v8
	v_mov_b32_e32 v22, v8
	s_nop 1
	v_permlane16_swap_b32_e32 v240, v22
	s_nop 1
	v_mov_b32_dpp v22, v240 quad_perm:[0,1,2,3] row_mask:0xa bank_mask:0xf
	v_mov_b32_e32 v240, v9
	v_mov_b32_e32 v23, v9
	s_nop 1
	v_permlane16_swap_b32_e32 v240, v23
	s_nop 1
	v_mov_b32_dpp v23, v240 quad_perm:[0,1,2,3] row_mask:0xa bank_mask:0xf
	s_waitcnt lgkmcnt(3)
; DI float shx(float v, int m, int lane) { return __builtin_bit_cast(float, __builtin_amdgcn_ds_bpermute((lane ^ m) << 2, __builtin_bit_cast(int, v))); }
; template <int PR>
; DI void prep_rows(const int lane, const Params& p, int l, int which, int rbeg, int rend, int gw, int nw) {
;     ...
;             for (int o = 32; o >= 1; o >>= 1)
; #pragma unroll
;                 for (int rr = 0; rr < PR; ++rr) sm[rr] += shx(sm[rr], o, lane);
; #pragma unroll
;             for (int rr = 0; rr < PR; ++rr) { const float mean = sm[rr] * (1.f / 1024.f); sm[rr] = mean; float q = 0.f;
; #pragma unroll
;                 for (int i = 0; i < 4; ++i) { v[rr][i] -= mean; q += v[rr][i][0] * v[rr][i][0] + v[rr][i][1] * v[rr][i][1] + v[rr][i][2] * v[rr][i][2] + v[rr][i][3] * v[rr][i][3]; }
	v_add_f32_e32 v18, v18, v28
	s_waitcnt lgkmcnt(2)
	v_add_f32_e32 v19, v19, v29
	v_mov_b32_e32 v240, v18
	v_mov_b32_e32 v28, v18
	s_nop 1
	v_permlane16_swap_b32_e32 v240, v28
	s_nop 1
	v_mov_b32_dpp v28, v240 quad_perm:[0,1,2,3] row_mask:0xa bank_mask:0xf
	v_mov_b32_e32 v240, v19
	v_mov_b32_e32 v29, v19
	s_nop 1
	v_permlane16_swap_b32_e32 v240, v29
	s_nop 1
	v_mov_b32_dpp v29, v240 quad_perm:[0,1,2,3] row_mask:0xa bank_mask:0xf
	s_waitcnt lgkmcnt(3)
	v_add_f32_e32 v8, v8, v22
	s_waitcnt lgkmcnt(2)
	v_add_f32_e32 v9, v9, v23
	s_nop 1
	v_mov_b32_dpp v22, v8 row_ror:8 row_mask:0xf bank_mask:0xf
	s_nop 1
	v_mov_b32_dpp v23, v9 row_ror:8 row_mask:0xf bank_mask:0xf
	s_waitcnt lgkmcnt(3)
	v_add_f32_e32 v18, v18, v28
	s_waitcnt lgkmcnt(2)
	v_add_f32_e32 v19, v19, v29
	s_nop 1
	v_mov_b32_dpp v28, v18 row_ror:8 row_mask:0xf bank_mask:0xf
	s_nop 1
	v_mov_b32_dpp v29, v19 row_ror:8 row_mask:0xf bank_mask:0xf
	s_waitcnt lgkmcnt(3)
	v_add_f32_e32 v8, v8, v22
	s_waitcnt lgkmcnt(2)
	v_add_f32_e32 v9, v9, v23
	s_nop 1
	v_mov_b32_dpp v22, v8 row_shl:4 row_mask:0xf bank_mask:0x5
	v_mov_b32_dpp v22, v8 row_shr:4 row_mask:0xf bank_mask:0xa
	s_nop 1
	v_mov_b32_dpp v23, v9 row_shl:4 row_mask:0xf bank_mask:0x5
	v_mov_b32_dpp v23, v9 row_shr:4 row_mask:0xf bank_mask:0xa
	s_waitcnt lgkmcnt(3)
	v_add_f32_e32 v18, v18, v28
	s_waitcnt lgkmcnt(2)
	v_add_f32_e32 v19, v19, v29
	s_nop 1
	v_mov_b32_dpp v28, v18 row_shl:4 row_mask:0xf bank_mask:0x5
	v_mov_b32_dpp v28, v18 row_shr:4 row_mask:0xf bank_mask:0xa
	s_nop 1
	v_mov_b32_dpp v29, v19 row_shl:4 row_mask:0xf bank_mask:0x5
	v_mov_b32_dpp v29, v19 row_shr:4 row_mask:0xf bank_mask:0xa
	s_waitcnt lgkmcnt(3)
	v_add_f32_e32 v8, v8, v22
	s_waitcnt lgkmcnt(2)
	v_add_f32_e32 v9, v9, v23
	s_nop 1
	v_mov_b32_dpp v22, v8 quad_perm:[2,3,0,1] row_mask:0xf bank_mask:0xf
	s_nop 1
	v_mov_b32_dpp v23, v9 quad_perm:[2,3,0,1] row_mask:0xf bank_mask:0xf
	s_waitcnt lgkmcnt(3)
	v_add_f32_e32 v18, v18, v28
	s_waitcnt lgkmcnt(2)
	v_add_f32_e32 v19, v19, v29
	s_nop 1
	v_mov_b32_dpp v28, v18 quad_perm:[2,3,0,1] row_mask:0xf bank_mask:0xf
	s_nop 1
	v_mov_b32_dpp v29, v19 quad_perm:[2,3,0,1] row_mask:0xf bank_mask:0xf
	s_waitcnt lgkmcnt(3)
	v_add_f32_e32 v8, v8, v22
	s_waitcnt lgkmcnt(2)
	v_add_f32_e32 v9, v9, v23
	s_nop 1
	v_mov_b32_dpp v22, v8 quad_perm:[1,0,3,2] row_mask:0xf bank_mask:0xf
	s_nop 1
	v_mov_b32_dpp v23, v9 quad_perm:[1,0,3,2] row_mask:0xf bank_mask:0xf
	s_waitcnt lgkmcnt(3)
	v_add_f32_e32 v18, v18, v28
	s_waitcnt lgkmcnt(2)
	v_add_f32_e32 v19, v19, v29
	s_nop 1
	v_mov_b32_dpp v28, v18 quad_perm:[1,0,3,2] row_mask:0xf bank_mask:0xf
	s_nop 1
	v_mov_b32_dpp v29, v19 quad_perm:[1,0,3,2] row_mask:0xf bank_mask:0xf
	s_waitcnt lgkmcnt(3)
	v_add_f32_e32 v8, v8, v22
	s_waitcnt lgkmcnt(2)
	v_add_f32_e32 v9, v9, v23
	v_fmac_f32_e32 v39, 0xba800000, v8
	v_fmac_f32_e32 v31, 0xba800000, v8
	v_fmac_f32_e32 v38, 0xba800000, v8
	v_fmac_f32_e32 v30, 0xba800000, v8
	v_fmac_f32_e32 v45, 0xba800000, v8
	v_fmac_f32_e32 v44, 0xba800000, v8
	v_fmac_f32_e32 v63, 0xba800000, v9
	v_fmac_f32_e32 v62, 0xba800000, v9
	v_fmac_f32_e32 v59, 0xba800000, v8
	v_fmac_f32_e32 v58, 0xba800000, v8
	v_fmac_f32_e32 v11, 0xba800000, v9
	v_fmac_f32_e32 v10, 0xba800000, v9
	v_fmac_f32_e32 v85, 0xba800000, v9
	v_fmac_f32_e32 v84, 0xba800000, v9
	s_waitcnt lgkmcnt(1)
	v_add_f32_e32 v65, v18, v28
	s_waitcnt lgkmcnt(0)
	v_add_f32_e32 v94, v19, v29
	v_mov_b32_e32 v46, v30
	v_mov_b32_e32 v48, v31
	v_mov_b32_e32 v114, v31
	v_mov_b32_e32 v115, v30
	v_mov_b32_e32 v22, v39
	v_mov_b32_e32 v23, v38
	v_pk_mul_f32 v[28:29], v[44:45], v[44:45]
	v_mov_b32_e32 v30, v63
	v_mov_b32_e32 v31, v62
	v_fmac_f32_e32 v43, 0xba800000, v8
	v_fmac_f32_e32 v41, 0xba800000, v8
	v_fmac_f32_e32 v42, 0xba800000, v8
	v_fmac_f32_e32 v40, 0xba800000, v8
	v_fmac_f32_e32 v81, 0xba800000, v9
	v_fmac_f32_e32 v79, 0xba800000, v9
	v_fmac_f32_e32 v78, 0xba800000, v9
	v_fmac_f32_e32 v83, 0xba800000, v9
	v_fmac_f32_e32 v82, 0xba800000, v9
	v_mov_b32_e32 v56, v59
	v_mov_b32_e32 v54, v58
	v_mov_b32_e32 v35, v62
	v_mov_b32_e32 v37, v63
	v_mov_b32_e32 v116, v11
	v_mov_b32_e32 v117, v10
	v_pk_mul_f32 v[62:63], v[84:85], v[84:85]
	v_fmac_f32_e32 v107, 0xba800000, v65
	v_fmac_f32_e32 v91, 0xba800000, v65
	v_fmac_f32_e32 v90, 0xba800000, v65
	v_fmac_f32_e32 v3, 0xba800000, v65
	v_fmac_f32_e32 v2, 0xba800000, v65
	v_fmac_f32_e32 v113, 0xba800000, v94
	v_fmac_f32_e32 v25, 0xba800000, v94
	v_fmac_f32_e32 v112, 0xba800000, v94
	v_fmac_f32_e32 v24, 0xba800000, v94
	v_pk_mul_f32 v[130:131], v[22:23], v[22:23]
	v_pk_fma_f32 v[132:133], v[58:59], v[58:59], v[28:29]
	v_pk_mul_f32 v[58:59], v[30:31], v[30:31]
	v_fmac_f32_e32 v109, 0xba800000, v8
	v_fmac_f32_e32 v61, 0xba800000, v8
	v_fmac_f32_e32 v108, 0xba800000, v8
	v_fmac_f32_e32 v60, 0xba800000, v8
	v_fmac_f32_e32 v80, 0xba800000, v9
	v_fmac_f32_e32 v5, 0xba800000, v9
	v_fmac_f32_e32 v7, 0xba800000, v9
	v_fmac_f32_e32 v4, 0xba800000, v9
	v_fmac_f32_e32 v6, 0xba800000, v9
	v_mov_b32_e32 v50, v40
	v_mov_b32_e32 v51, v42
	v_mov_b32_e32 v52, v41
	v_mov_b32_e32 v53, v43
	v_mov_b32_e32 v122, v41
	v_mov_b32_e32 v123, v40
	v_mov_b32_e32 v8, v43
	v_mov_b32_e32 v9, v42
	v_mov_b32_e32 v34, v10
	v_mov_b32_e32 v36, v11
	v_mov_b32_e32 v40, v79
	v_mov_b32_e32 v41, v81
	v_mov_b32_e32 v10, v79
	v_mov_b32_e32 v11, v78
	v_mov_b32_e32 v18, v81
	v_mov_b32_e32 v42, v82
	v_mov_b32_e32 v43, v84
	v_fmac_f32_e32 v89, 0xba800000, v65
	v_fmac_f32_e32 v87, 0xba800000, v65
	v_fmac_f32_e32 v106, 0xba800000, v65
	v_fmac_f32_e32 v88, 0xba800000, v65
	v_fmac_f32_e32 v1, 0xba800000, v65
	v_fmac_f32_e32 v0, 0xba800000, v65
	v_fmac_f32_e32 v27, 0xba800000, v94
	v_fmac_f32_e32 v21, 0xba800000, v94
; DI float shx(float v, int m, int lane) { return __builtin_bit_cast(float, __builtin_amdgcn_ds_bpermute((lane ^ m) << 2, __builtin_bit_cast(int, v))); }
; template <int PR>
; DI void prep_rows(const int lane, const Params& p, int l, int which, int rbeg, int rend, int gw, int nw) {
;     ...
;             for (int rr = 0; rr < PR; ++rr) { const float mean = sm[rr] * (1.f / 1024.f); sm[rr] = mean; float q = 0.f;
; #pragma unroll
;                 for (int i = 0; i < 4; ++i) { v[rr][i] -= mean; q += v[rr][i][0] * v[rr][i][0] + v[rr][i][1] * v[rr][i][1] + v[rr][i][2] * v[rr][i][2] + v[rr][i][3] * v[rr][i][3]; }
;                 sq[rr] = q; }
; #pragma unroll
;             for (int o = 32; o >= 1; o >>= 1)
; #pragma unroll
;                 for (int rr = 0; rr < PR; ++rr) sq[rr] += shx(sq[rr], o, lane);
;     ...
;             for (int i = 0; i < 4; ++i) { const f32x4 g = *(const f32x4*)(lg + PCOL(i)), b = *(const f32x4*)(lb + PCOL(i));
	v_fmac_f32_e32 v26, 0xba800000, v94
	v_fmac_f32_e32 v20, 0xba800000, v94
	v_fmac_f32_e32 v17, 0xba800000, v94
	v_fmac_f32_e32 v93, 0xba800000, v94
	v_fmac_f32_e32 v121, 0xba800000, v94
	v_fmac_f32_e32 v119, 0xba800000, v94
	v_fmac_f32_e32 v16, 0xba800000, v94
	v_fmac_f32_e32 v92, 0xba800000, v94
	v_fmac_f32_e32 v120, 0xba800000, v94
	v_fmac_f32_e32 v118, 0xba800000, v94
	v_pk_fma_f32 v[94:95], v[82:83], v[82:83], v[62:63]
	v_mov_b32_e32 v102, v90
	v_mov_b32_e32 v104, v91
	v_mov_b32_e32 v105, v107
	v_mov_b32_e32 v28, v91
	v_mov_b32_e32 v29, v90
	v_mov_b32_e32 v22, v107
	v_mov_b32_e32 v79, v24
	v_mov_b32_e32 v81, v25
	v_mov_b32_e32 v90, v25
	v_mov_b32_e32 v91, v24
	v_mov_b32_e32 v82, v112
	v_mov_b32_e32 v84, v113
	v_mov_b32_e32 v24, v113
	v_mov_b32_e32 v25, v112
	v_mov_b32_e32 v107, v3
	v_pk_fma_f32 v[112:113], v[114:115], v[114:115], v[130:131]
	v_mov_b32_e32 v115, v2
	v_pk_mul_f32 v[2:3], v[2:3], v[2:3]
	v_pk_fma_f32 v[116:117], v[116:117], v[116:117], v[58:59]
	v_fmac_f32_e32 v86, 0xba800000, v65
	v_mov_b32_e32 v100, v87
	v_mov_b32_e32 v101, v89
	v_mov_b32_e32 v96, v87
	v_mov_b32_e32 v110, v89
	v_mov_b32_e32 v111, v88
	v_mov_b32_e32 v103, v106
	v_mov_b32_e32 v23, v106
	v_mov_b32_e32 v106, v1
	v_mov_b32_e32 v114, v0
	v_mov_b32_e32 v87, v121
	v_pk_fma_f32 v[62:63], v[0:1], v[0:1], v[2:3]
	v_mov_b32_e32 v89, v120
	v_pk_mul_f32 v[0:1], v[120:121], v[120:121]
	v_pk_fma_f32 v[120:121], v[10:11], v[10:11], v[116:117]
	v_pk_fma_f32 v[10:11], v[6:7], v[6:7], v[94:95]
	v_mov_b32_e32 v47, v38
	v_mov_b32_e32 v49, v39
	v_mov_b32_e32 v57, v45
	v_mov_b32_e32 v55, v44
	v_mov_b32_e32 v38, v78
	v_mov_b32_e32 v39, v80
	v_mov_b32_e32 v19, v80
	v_mov_b32_e32 v44, v83
	v_mov_b32_e32 v45, v85
	v_mov_b32_e32 v99, v88
	v_mov_b32_e32 v97, v86
	v_mov_b32_e32 v78, v20
	v_mov_b32_e32 v80, v21
	v_mov_b32_e32 v30, v21
	v_mov_b32_e32 v31, v20
	v_mov_b32_e32 v83, v26
	v_mov_b32_e32 v85, v27
	v_mov_b32_e32 v20, v27
	v_mov_b32_e32 v21, v26
	v_mov_b32_e32 v88, v118
	v_pk_fma_f32 v[26:27], v[118:119], v[118:119], v[0:1]
	v_mov_b32_e32 v116, v7
	v_mov_b32_e32 v118, v6
	v_pk_mul_f32 v[6:7], v[110:111], v[110:111]
	v_pk_fma_f32 v[94:95], v[4:5], v[4:5], v[10:11]
	v_pk_mul_f32 v[10:11], v[90:91], v[90:91]
	v_pk_fma_f32 v[112:113], v[122:123], v[122:123], v[112:113]
	v_pk_fma_f32 v[96:97], v[96:97], v[96:97], v[6:7]
	v_pk_fma_f32 v[30:31], v[30:31], v[30:31], v[10:11]
	v_fmac_f32_e32 v15, 0xba800000, v65
	v_fmac_f32_e32 v14, 0xba800000, v65
	v_pk_fma_f32 v[0:1], v[60:61], v[60:61], v[132:133]
	v_pk_fma_f32 v[110:111], v[8:9], v[8:9], v[112:113]
	v_pk_fma_f32 v[18:19], v[18:19], v[18:19], v[120:121]
	v_pk_fma_f32 v[28:29], v[28:29], v[28:29], v[96:97]
	v_pk_fma_f32 v[24:25], v[24:25], v[24:25], v[30:31]
	v_pk_fma_f32 v[26:27], v[92:93], v[92:93], v[26:27]
	v_fmac_f32_e32 v13, 0xba800000, v65
	v_fmac_f32_e32 v12, 0xba800000, v65
	v_mov_b32_e32 v58, v61
	v_mov_b32_e32 v59, v109
	v_mov_b32_e32 v61, v108
	v_pk_fma_f32 v[108:109], v[108:109], v[108:109], v[0:1]
	v_pk_fma_f32 v[62:63], v[14:15], v[14:15], v[62:63]
	v_pk_fma_f32 v[96:97], v[16:17], v[16:17], v[26:27]
	v_mov_b32_e32 v26, v18
	v_mov_b32_e32 v27, v110
	v_mov_b32_e32 v110, v19
	v_pk_fma_f32 v[28:29], v[22:23], v[22:23], v[28:29]
	v_pk_fma_f32 v[20:21], v[20:21], v[20:21], v[24:25]
	v_mov_b32_e32 v112, v95
	v_mov_b32_e32 v113, v109
	v_pk_fma_f32 v[62:63], v[12:13], v[12:13], v[62:63]
	v_pk_add_f32 v[24:25], v[26:27], v[110:111]
	v_mov_b32_e32 v26, v20
	v_mov_b32_e32 v27, v28
	v_mov_b32_e32 v28, v21
	v_mov_b32_e32 v98, v86
	v_mov_b32_e32 v86, v119
	global_load_dwordx4 v[0:3], v[66:67], off offset:16
	v_mov_b32_e32 v117, v5
	v_mov_b32_e32 v119, v4
	global_load_dwordx4 v[4:7], v[66:67], off
	global_load_dwordx4 v[8:11], v[68:69], off offset:16
	v_mov_b32_e32 v95, v108
	v_mov_b32_e32 v120, v15
	v_mov_b32_e32 v121, v13
	v_mov_b32_e32 v122, v14
	v_mov_b32_e32 v123, v12
	global_load_dwordx4 v[12:15], v[68:69], off
	v_mov_b32_e32 v30, v97
	v_mov_b32_e32 v31, v63
	v_mov_b32_e32 v97, v62
	v_pk_add_f32 v[62:63], v[112:113], v[24:25]
	v_pk_add_f32 v[28:29], v[26:27], v[28:29]
	v_mov_b32_e32 v90, v93
	v_mov_b32_e32 v91, v17
	v_mov_b32_e32 v93, v16
	global_load_dwordx4 v[16:19], v[70:71], off offset:16
	global_load_dwordx4 v[20:23], v[70:71], off
	global_load_dwordx4 v[24:27], v[72:73], off offset:16
	v_pk_add_f32 v[62:63], v[94:95], v[62:63]
	v_pk_add_f32 v[94:95], v[30:31], v[28:29]
	global_load_dwordx4 v[28:31], v[72:73], off
	v_pk_add_f32 v[94:95], v[96:97], v[94:95]
	v_mov_b32_e32 v240, v63
	v_mov_b32_e32 v97, v63
	s_nop 1
	v_permlane32_swap_b32_e32 v240, v97
	s_nop 1
	v_mov_b32_dpp v97, v240 quad_perm:[0,1,2,3] row_mask:0xc bank_mask:0xf
	v_mov_b32_e32 v240, v62
	v_mov_b32_e32 v96, v62
	s_nop 1
	v_permlane32_swap_b32_e32 v240, v96
	s_nop 1
	v_mov_b32_dpp v96, v240 quad_perm:[0,1,2,3] row_mask:0xc bank_mask:0xf
	s_waitcnt lgkmcnt(0)
	v_pk_add_f32 v[62:63], v[62:63], v[96:97]
	v_mov_b32_e32 v240, v95
	v_mov_b32_e32 v97, v95
	s_nop 1
	v_permlane32_swap_b32_e32 v240, v97
	s_nop 1
	v_mov_b32_dpp v97, v240 quad_perm:[0,1,2,3] row_mask:0xc bank_mask:0xf
	v_mov_b32_e32 v240, v94
	v_mov_b32_e32 v96, v94
	s_nop 1
	v_permlane32_swap_b32_e32 v240, v96
	s_nop 1
	v_mov_b32_dpp v96, v240 quad_perm:[0,1,2,3] row_mask:0xc bank_mask:0xf
	s_waitcnt lgkmcnt(0)
	v_pk_add_f32 v[94:95], v[94:95], v[96:97]
	v_mov_b32_e32 v240, v63
	v_mov_b32_e32 v97, v63
	s_nop 1
	v_permlane16_swap_b32_e32 v240, v97
	s_nop 1
	v_mov_b32_dpp v97, v240 quad_perm:[0,1,2,3] row_mask:0xa bank_mask:0xf
	v_mov_b32_e32 v240, v62
	v_mov_b32_e32 v96, v62
	s_nop 1
	v_permlane16_swap_b32_e32 v240, v96
	s_nop 1
	v_mov_b32_dpp v96, v240 quad_perm:[0,1,2,3] row_mask:0xa bank_mask:0xf
	s_waitcnt lgkmcnt(0)
; DI float shx(float v, int m, int lane) { return __builtin_bit_cast(float, __builtin_amdgcn_ds_bpermute((lane ^ m) << 2, __builtin_bit_cast(int, v))); }
; template <int PR>
; DI void prep_rows(const int lane, const Params& p, int l, int which, int rbeg, int rend, int gw, int nw) {
;     ...
;             for (int o = 32; o >= 1; o >>= 1)
; #pragma unroll
;                 for (int rr = 0; rr < PR; ++rr) sq[rr] += shx(sq[rr], o, lane);
; #pragma unroll
;             for (int rr = 0; rr < PR; ++rr) { sq[rr] = rsqrtf(sq[rr] * (1.f / 1024.f) + LN_EPS);
;                 if (which != 2 && lane == 0) { P_WSF(OFF_STATS)[2 * (row + rr)] = sm[rr]; P_WSF(OFF_STATS)[2 * (row + rr) + 1] = sq[rr]; } }
; #pragma unroll
;             for (int i = 0; i < 4; ++i) { const f32x4 g = *(const f32x4*)(lg + PCOL(i)), b = *(const f32x4*)(lb + PCOL(i));
; #pragma unroll
;                 for (int rr = 0; rr < PR; ++rr) v[rr][i] = v[rr][i] * sq[rr] * g + b; }
	v_pk_add_f32 v[62:63], v[62:63], v[96:97]
	v_mov_b32_e32 v240, v95
	v_mov_b32_e32 v97, v95
	s_nop 1
	v_permlane16_swap_b32_e32 v240, v97
	s_nop 1
	v_mov_b32_dpp v97, v240 quad_perm:[0,1,2,3] row_mask:0xa bank_mask:0xf
	v_mov_b32_e32 v240, v94
	v_mov_b32_e32 v96, v94
	s_nop 1
	v_permlane16_swap_b32_e32 v240, v96
	s_nop 1
	v_mov_b32_dpp v96, v240 quad_perm:[0,1,2,3] row_mask:0xa bank_mask:0xf
	s_waitcnt lgkmcnt(0)
	v_pk_add_f32 v[94:95], v[94:95], v[96:97]
	s_nop 1
	v_mov_b32_dpp v97, v63 row_ror:8 row_mask:0xf bank_mask:0xf
	s_nop 1
	v_mov_b32_dpp v96, v62 row_ror:8 row_mask:0xf bank_mask:0xf
	s_waitcnt lgkmcnt(0)
	v_pk_add_f32 v[62:63], v[62:63], v[96:97]
	s_nop 1
	v_mov_b32_dpp v97, v95 row_ror:8 row_mask:0xf bank_mask:0xf
	s_nop 1
	v_mov_b32_dpp v96, v94 row_ror:8 row_mask:0xf bank_mask:0xf
	s_waitcnt lgkmcnt(0)
	v_pk_add_f32 v[94:95], v[94:95], v[96:97]
	s_nop 1
	v_mov_b32_dpp v97, v63 row_shl:4 row_mask:0xf bank_mask:0x5
	v_mov_b32_dpp v97, v63 row_shr:4 row_mask:0xf bank_mask:0xa
	s_nop 1
	v_mov_b32_dpp v96, v62 row_shl:4 row_mask:0xf bank_mask:0x5
	v_mov_b32_dpp v96, v62 row_shr:4 row_mask:0xf bank_mask:0xa
	s_waitcnt lgkmcnt(0)
	v_pk_add_f32 v[62:63], v[62:63], v[96:97]
	s_nop 1
	v_mov_b32_dpp v97, v95 row_shl:4 row_mask:0xf bank_mask:0x5
	v_mov_b32_dpp v97, v95 row_shr:4 row_mask:0xf bank_mask:0xa
	s_nop 1
	v_mov_b32_dpp v96, v94 row_shl:4 row_mask:0xf bank_mask:0x5
	v_mov_b32_dpp v96, v94 row_shr:4 row_mask:0xf bank_mask:0xa
	s_waitcnt lgkmcnt(0)
	v_pk_add_f32 v[94:95], v[94:95], v[96:97]
	s_nop 1
	v_mov_b32_dpp v97, v63 quad_perm:[2,3,0,1] row_mask:0xf bank_mask:0xf
	s_nop 1
	v_mov_b32_dpp v96, v62 quad_perm:[2,3,0,1] row_mask:0xf bank_mask:0xf
	s_waitcnt lgkmcnt(0)
	v_pk_add_f32 v[62:63], v[62:63], v[96:97]
	s_nop 1
	v_mov_b32_dpp v97, v95 quad_perm:[2,3,0,1] row_mask:0xf bank_mask:0xf
	s_nop 1
	v_mov_b32_dpp v96, v94 quad_perm:[2,3,0,1] row_mask:0xf bank_mask:0xf
	s_waitcnt lgkmcnt(0)
	v_pk_add_f32 v[94:95], v[94:95], v[96:97]
	s_nop 1
	v_mov_b32_dpp v97, v63 quad_perm:[1,0,3,2] row_mask:0xf bank_mask:0xf
	s_nop 1
	v_mov_b32_dpp v96, v62 quad_perm:[1,0,3,2] row_mask:0xf bank_mask:0xf
	s_waitcnt lgkmcnt(0)
	v_pk_add_f32 v[62:63], v[62:63], v[96:97]
	s_nop 1
	v_mov_b32_dpp v97, v95 quad_perm:[1,0,3,2] row_mask:0xf bank_mask:0xf
	s_nop 1
	v_mov_b32_dpp v96, v94 quad_perm:[1,0,3,2] row_mask:0xf bank_mask:0xf
	v_pk_fma_f32 v[62:63], v[62:63], s[20:21], v[32:33] op_sel_hi:[1,0,0]
	s_waitcnt lgkmcnt(0)
	v_pk_add_f32 v[96:97], v[94:95], v[96:97]
	v_mul_f32_e32 v65, 0x4b800000, v63
	v_cmp_gt_f32_e64 s[4:5], s81, v63
	v_add_co_u32_e32 v94, vcc, s0, v74
	s_nop 0
	v_cndmask_b32_e64 v63, v63, v65, s[4:5]
	v_rsq_f32_e32 v63, v63
	v_addc_co_u32_e32 v95, vcc, -1, v75, vcc
	v_pk_fma_f32 v[32:33], v[96:97], s[20:21], v[32:33] op_sel_hi:[1,0,0]
	v_mul_f32_e32 v96, 0x4b800000, v62
	v_cmp_gt_f32_e64 s[2:3], s81, v62
	v_mul_f32_e32 v65, 0x4b800000, v32
	v_cmp_gt_f32_e32 vcc, s81, v32
	v_cndmask_b32_e64 v108, v62, v96, s[2:3]
	v_mul_f32_e32 v62, 0x4b800000, v33
	v_cmp_gt_f32_e64 s[0:1], s81, v33
	v_cndmask_b32_e32 v65, v32, v65, vcc
	v_mul_f32_e32 v32, 0x45800000, v63
	v_cndmask_b32_e64 v33, v33, v62, s[0:1]
	v_cndmask_b32_e64 v32, v63, v32, s[4:5]
	v_pk_mul_f32 v[48:49], v[48:49], v[32:33] op_sel_hi:[1,0]
	v_pk_mul_f32 v[52:53], v[52:53], v[32:33] op_sel_hi:[1,0]
	v_pk_mul_f32 v[62:63], v[46:47], v[32:33] op_sel_hi:[1,0]
	v_pk_mul_f32 v[46:47], v[50:51], v[32:33] op_sel_hi:[1,0]
	v_pk_mul_f32 v[50:51], v[56:57], v[32:33] op_sel_hi:[1,0]
	v_pk_mul_f32 v[56:57], v[58:59], v[32:33] op_sel_hi:[1,0]
	v_pk_mul_f32 v[58:59], v[54:55], v[32:33] op_sel_hi:[1,0]
	v_pk_mul_f32 v[60:61], v[60:61], v[32:33] op_sel_hi:[1,0]
	v_rsq_f32_e32 v32, v108
	v_rsq_f32_e32 v132, v33
	v_rsq_f32_e32 v65, v65
	s_movk_i32 s4, 0xe000
	v_mul_f32_e32 v33, 0x45800000, v32
	v_cndmask_b32_e64 v32, v32, v33, s[2:3]
	v_pk_mul_f32 v[40:41], v[40:41], v[32:33] op_sel_hi:[1,0]
	v_pk_mul_f32 v[108:109], v[34:35], v[32:33] op_sel_hi:[1,0]
	v_pk_mul_f32 v[116:117], v[116:117], v[32:33] op_sel_hi:[1,0]
	s_waitcnt vmcnt(4)
	v_pk_fma_f32 v[34:35], v[6:7], v[40:41], v[14:15]
	v_pk_fma_f32 v[40:41], v[0:1], v[108:109], v[8:9]
	v_mul_f32_e32 v108, 0x45800000, v132
	v_pk_mul_f32 v[110:111], v[38:39], v[32:33] op_sel_hi:[1,0]
	v_pk_mul_f32 v[112:113], v[44:45], v[32:33] op_sel_hi:[1,0]
	v_pk_fma_f32 v[38:39], v[6:7], v[52:53], v[14:15]
	s_waitcnt vmcnt(0)
; template <int PR>
; DI void prep_rows(const int lane, const Params& p, int l, int which, int rbeg, int rend, int gw, int nw) {
;     ...
;             for (int i = 0; i < 4; ++i) { const f32x4 g = *(const f32x4*)(lg + PCOL(i)), b = *(const f32x4*)(lb + PCOL(i));
; #pragma unroll
;                 for (int rr = 0; rr < PR; ++rr) v[rr][i] = v[rr][i] * sq[rr] * g + b; }
;         }
;         if (which == 2) {
; #pragma unroll
;             for (int rr = 0; rr < PR; ++rr)
; #pragma unroll
;                 for (int i = 0; i < 4; ++i) *(f32x4*)(P_OUT + (size_t)(row + rr) * 1024 + PCOL(i)) = v[rr][i];
	v_pk_fma_f32 v[52:53], v[20:21], v[50:51], v[28:29]
	v_pk_fma_f32 v[50:51], v[22:23], v[116:117], v[30:31]
	v_cndmask_b32_e64 v116, v132, v108, s[0:1]
	v_pk_mul_f32 v[54:55], v[36:37], v[32:33] op_sel_hi:[1,0]
	v_pk_fma_f32 v[36:37], v[4:5], v[48:49], v[12:13]
	v_pk_fma_f32 v[48:49], v[20:21], v[112:113], v[28:29]
	v_pk_mul_f32 v[112:113], v[104:105], v[116:117] op_sel_hi:[1,0]
	v_pk_mul_f32 v[104:105], v[98:99], v[116:117] op_sel_hi:[1,0]
	v_pk_mul_f32 v[98:99], v[114:115], v[116:117] op_sel_hi:[1,0]
	v_add_co_u32_e64 v114, s[0:1], s13, v74
	v_pk_mul_f32 v[130:131], v[42:43], v[32:33] op_sel_hi:[1,0]
	v_pk_fma_f32 v[42:43], v[2:3], v[110:111], v[10:11]
	v_pk_mul_f32 v[108:109], v[100:101], v[116:117] op_sel_hi:[1,0]
	v_pk_mul_f32 v[110:111], v[102:103], v[116:117] op_sel_hi:[1,0]
	v_pk_mul_f32 v[100:101], v[106:107], v[116:117] op_sel_hi:[1,0]
	v_pk_mul_f32 v[106:107], v[120:121], v[116:117] op_sel_hi:[1,0]
	v_pk_mul_f32 v[102:103], v[122:123], v[116:117] op_sel_hi:[1,0]
	v_addc_co_u32_e64 v115, s[0:1], -1, v75, s[0:1]
	v_mul_f32_e32 v116, 0x45800000, v65
	v_add_co_u32_e64 v96, s[4:5], s4, v74
	v_pk_mul_f32 v[118:119], v[118:119], v[32:33] op_sel_hi:[1,0]
	v_pk_fma_f32 v[32:33], v[4:5], v[54:55], v[12:13]
	v_cmp_lt_i32_e64 s[0:1], s15, v64
	v_cndmask_b32_e32 v116, v65, v116, vcc
	v_addc_co_u32_e64 v97, s[4:5], -1, v75, s[4:5]
	v_pk_fma_f32 v[46:47], v[2:3], v[46:47], v[10:11]
	v_pk_fma_f32 v[44:45], v[0:1], v[62:63], v[8:9]
	v_pk_fma_f32 v[54:55], v[22:23], v[56:57], v[30:31]
	v_pk_fma_f32 v[62:63], v[18:19], v[60:61], v[26:27]
	v_pk_fma_f32 v[60:61], v[16:17], v[58:59], v[24:25]
	v_pk_fma_f32 v[58:59], v[18:19], v[118:119], v[26:27]
	v_pk_fma_f32 v[56:57], v[16:17], v[130:131], v[24:25]
	s_or_b64 s[10:11], s[0:1], s[10:11]
	v_pk_mul_f32 v[80:81], v[80:81], v[116:117] op_sel_hi:[1,0]
	v_pk_mul_f32 v[84:85], v[84:85], v[116:117] op_sel_hi:[1,0]
	v_pk_mul_f32 v[78:79], v[78:79], v[116:117] op_sel_hi:[1,0]
	v_pk_mul_f32 v[82:83], v[82:83], v[116:117] op_sel_hi:[1,0]
	v_pk_mul_f32 v[86:87], v[86:87], v[116:117] op_sel_hi:[1,0]
	v_pk_mul_f32 v[90:91], v[90:91], v[116:117] op_sel_hi:[1,0]
	v_pk_mul_f32 v[88:89], v[88:89], v[116:117] op_sel_hi:[1,0]
	v_pk_mul_f32 v[92:93], v[92:93], v[116:117] op_sel_hi:[1,0]
	global_store_dwordx4 v[114:115], v[36:39], off offset:-2064
	global_store_dwordx4 v[114:115], v[44:47], off offset:-2048
	global_store_dwordx4 v[114:115], v[52:55], off offset:-16
	global_store_dwordx4 v[74:75], v[60:63], off offset:-4096
	global_store_dwordx4 v[74:75], v[32:35], off offset:-2064
	global_store_dwordx4 v[74:75], v[40:43], off offset:-2048
	global_store_dwordx4 v[74:75], v[48:51], off offset:-16
	global_store_dwordx4 v[74:75], v[56:59], off
	v_lshl_add_u64 v[74:75], v[74:75], 0, s[16:17]
	v_pk_fma_f32 v[34:35], v[6:7], v[112:113], v[14:15]
	v_pk_fma_f32 v[32:33], v[4:5], v[108:109], v[12:13]
	v_pk_fma_f32 v[6:7], v[6:7], v[84:85], v[14:15]
	v_pk_fma_f32 v[4:5], v[4:5], v[80:81], v[12:13]
	v_pk_fma_f32 v[14:15], v[2:3], v[110:111], v[10:11]
	v_pk_fma_f32 v[12:13], v[0:1], v[104:105], v[8:9]
	v_pk_fma_f32 v[2:3], v[2:3], v[82:83], v[10:11]
	v_pk_fma_f32 v[0:1], v[0:1], v[78:79], v[8:9]
	v_pk_fma_f32 v[10:11], v[22:23], v[106:107], v[30:31]
	v_pk_fma_f32 v[8:9], v[20:21], v[100:101], v[28:29]
	v_pk_fma_f32 v[22:23], v[22:23], v[90:91], v[30:31]
	v_pk_fma_f32 v[20:21], v[20:21], v[86:87], v[28:29]
	v_pk_fma_f32 v[30:31], v[18:19], v[102:103], v[26:27]
	v_pk_fma_f32 v[28:29], v[16:17], v[98:99], v[24:25]
	v_pk_fma_f32 v[18:19], v[18:19], v[92:93], v[26:27]
	v_pk_fma_f32 v[16:17], v[16:17], v[88:89], v[24:25]
	global_store_dwordx4 v[94:95], v[32:35], off offset:-2064
	global_store_dwordx4 v[94:95], v[12:15], off offset:-2048
	global_store_dwordx4 v[94:95], v[8:11], off offset:-16
	global_store_dwordx4 v[96:97], v[28:31], off offset:-4096
	global_store_dwordx4 v[96:97], v[4:7], off offset:-2064
	global_store_dwordx4 v[96:97], v[0:3], off offset:-2048
	global_store_dwordx4 v[96:97], v[20:23], off offset:-16
	global_store_dwordx4 v[96:97], v[16:19], off
	s_andn2_b64 exec, exec, s[10:11]
	s_cbranch_execnz .LBB0_84

; DI float shx(float v, int m, int lane) { return __builtin_bit_cast(float, __builtin_amdgcn_ds_bpermute((lane ^ m) << 2, __builtin_bit_cast(int, v))); }
; template <int PR>
; DI void prep_rows(const int lane, const Params& p, int l, int which, int rbeg, int rend, int gw, int nw) {
;     ...
;             for (int rr = 0; rr < PR; ++rr) { float s = 0.f;
; #pragma unroll
;                 for (int i = 0; i < 4; ++i) s += v[rr][i][0] + v[rr][i][1] + v[rr][i][2] + v[rr][i][3];
;                 sm[rr] = s; }
; #pragma unroll
;             for (int o = 32; o >= 1; o >>= 1)
; #pragma unroll
;                 for (int rr = 0; rr < PR; ++rr) sm[rr] += shx(sm[rr], o, lane);
; #pragma unroll
;             for (int rr = 0; rr < PR; ++rr) { const float mean = sm[rr] * (1.f / 1024.f); sm[rr] = mean; float q = 0.f;
; #pragma unroll
;                 for (int i = 0; i < 4; ++i) { v[rr][i] -= mean; q += v[rr][i][0] * v[rr][i][0] + v[rr][i][1] * v[rr][i][1] + v[rr][i][2] * v[rr][i][2] + v[rr][i][3] * v[rr][i][3]; }
;                 sq[rr] = q; }
; #pragma unroll
;             for (int o = 32; o >= 1; o >>= 1)
; #pragma unroll
;                 for (int rr = 0; rr < PR; ++rr) sq[rr] += shx(sq[rr], o, lane);
; #pragma unroll
;             for (int rr = 0; rr < PR; ++rr) { sq[rr] = rsqrtf(sq[rr] * (1.f / 1024.f) + LN_EPS);
;                 if (which != 2 && lane == 0) { P_WSF(OFF_STATS)[2 * (row + rr)] = sm[rr]; P_WSF(OFF_STATS)[2 * (row + rr) + 1] = sq[rr]; } }
.LBB0_185:
	s_or_b64 exec, exec, s[10:11]
	v_mov_b32_e32 v8, v64
	v_mov_b32_e32 v9, v60
	v_mov_b32_e32 v10, v65
	v_mov_b32_e32 v11, v61
	v_pk_add_f32 v[8:9], v[8:9], v[10:11]
	v_mov_b32_e32 v10, v66
	v_mov_b32_e32 v11, v62
	v_pk_add_f32 v[8:9], v[10:11], v[8:9]
	v_mov_b32_e32 v10, v67
	v_mov_b32_e32 v11, v63
	v_pk_add_f32 v[8:9], v[10:11], v[8:9]
	v_mov_b32_e32 v10, v1
	v_add_f32_e32 v9, 0, v9
	v_add_f32_e32 v12, v8, v9
	v_mov_b32_e32 v8, v0
	v_mov_b32_e32 v9, v4
	v_mov_b32_e32 v11, v5
	v_pk_add_f32 v[8:9], v[8:9], v[10:11]
	v_mov_b32_e32 v10, v2
	v_mov_b32_e32 v11, v6
	v_pk_add_f32 v[8:9], v[10:11], v[8:9]
	v_mov_b32_e32 v10, v3
	v_mov_b32_e32 v11, v7
	v_pk_add_f32 v[8:9], v[10:11], v[8:9]
	s_nop 0
	v_add_f32_e32 v9, v9, v12
	v_add_f32_e32 v8, v8, v9
	v_mov_b32_e32 v240, v8
	v_mov_b32_e32 v9, v8
	s_nop 1
	v_permlane32_swap_b32_e32 v240, v9
	s_nop 1
	v_mov_b32_dpp v9, v240 quad_perm:[0,1,2,3] row_mask:0xc bank_mask:0xf
	s_waitcnt lgkmcnt(0)
	v_add_f32_e32 v8, v8, v9
	v_mov_b32_e32 v240, v8
	v_mov_b32_e32 v9, v8
	s_nop 1
	v_permlane16_swap_b32_e32 v240, v9
	s_nop 1
	v_mov_b32_dpp v9, v240 quad_perm:[0,1,2,3] row_mask:0xa bank_mask:0xf
	s_waitcnt lgkmcnt(0)
	v_add_f32_e32 v8, v8, v9
	s_nop 1
	v_mov_b32_dpp v9, v8 row_ror:8 row_mask:0xf bank_mask:0xf
	s_waitcnt lgkmcnt(0)
	v_add_f32_e32 v8, v8, v9
	s_nop 1
	v_mov_b32_dpp v9, v8 row_shl:4 row_mask:0xf bank_mask:0x5
	v_mov_b32_dpp v9, v8 row_shr:4 row_mask:0xf bank_mask:0xa
	s_waitcnt lgkmcnt(0)
	v_add_f32_e32 v8, v8, v9
	s_nop 1
	v_mov_b32_dpp v9, v8 quad_perm:[2,3,0,1] row_mask:0xf bank_mask:0xf
	s_waitcnt lgkmcnt(0)
	v_add_f32_e32 v8, v8, v9
	s_nop 1
	v_mov_b32_dpp v9, v8 quad_perm:[1,0,3,2] row_mask:0xf bank_mask:0xf
	s_waitcnt lgkmcnt(0)
	v_add_f32_e32 v9, v8, v9
	v_fmac_f32_e32 v61, 0xba800000, v9
	v_fmac_f32_e32 v65, 0xba800000, v9
	v_fmac_f32_e32 v60, 0xba800000, v9
	v_fmac_f32_e32 v64, 0xba800000, v9
	v_mov_b32_e32 v12, v61
	v_mov_b32_e32 v13, v65
	v_fmac_f32_e32 v62, 0xba800000, v9
	v_fmac_f32_e32 v66, 0xba800000, v9
	v_mov_b32_e32 v10, v60
	v_mov_b32_e32 v11, v64
	v_pk_mul_f32 v[12:13], v[12:13], v[12:13]
	v_fmac_f32_e32 v63, 0xba800000, v9
	v_fmac_f32_e32 v67, 0xba800000, v9
	v_pk_fma_f32 v[10:11], v[10:11], v[10:11], v[12:13]
	v_mov_b32_e32 v12, v62
	v_mov_b32_e32 v13, v66
	v_fmac_f32_e32 v5, 0xba800000, v9
	v_fmac_f32_e32 v1, 0xba800000, v9
	v_pk_fma_f32 v[10:11], v[12:13], v[12:13], v[10:11]
	v_mov_b32_e32 v12, v63
	v_mov_b32_e32 v13, v67
	v_fmac_f32_e32 v4, 0xba800000, v9
	v_fmac_f32_e32 v0, 0xba800000, v9
	v_mov_b32_e32 v14, v1
	v_mov_b32_e32 v15, v5
	v_pk_fma_f32 v[10:11], v[12:13], v[12:13], v[10:11]
	v_fmac_f32_e32 v6, 0xba800000, v9
	v_fmac_f32_e32 v2, 0xba800000, v9
	v_mov_b32_e32 v12, v0
	v_mov_b32_e32 v13, v4
	v_pk_mul_f32 v[14:15], v[14:15], v[14:15]
	v_fmac_f32_e32 v7, 0xba800000, v9
	v_fmac_f32_e32 v3, 0xba800000, v9
	v_pk_fma_f32 v[12:13], v[12:13], v[12:13], v[14:15]
	v_mov_b32_e32 v14, v2
	v_mov_b32_e32 v15, v6
	v_pk_fma_f32 v[12:13], v[14:15], v[14:15], v[12:13]
	v_mov_b32_e32 v14, v3
	v_mov_b32_e32 v15, v7
	v_pk_fma_f32 v[12:13], v[14:15], v[14:15], v[12:13]
	v_add_f32_e32 v8, v10, v11
	v_add_f32_e32 v8, v13, v8
	v_add_f32_e32 v8, v12, v8
	v_mov_b32_e32 v240, v8
	v_mov_b32_e32 v10, v8
	s_nop 1
	v_permlane32_swap_b32_e32 v240, v10
	s_nop 1
	v_mov_b32_dpp v10, v240 quad_perm:[0,1,2,3] row_mask:0xc bank_mask:0xf
	s_waitcnt lgkmcnt(0)
	v_add_f32_e32 v8, v8, v10
	v_mov_b32_e32 v240, v8
	v_mov_b32_e32 v10, v8
	s_nop 1
	v_permlane16_swap_b32_e32 v240, v10
	s_nop 1
	v_mov_b32_dpp v10, v240 quad_perm:[0,1,2,3] row_mask:0xa bank_mask:0xf
	s_waitcnt lgkmcnt(0)
	v_add_f32_e32 v8, v8, v10
	s_nop 1
	v_mov_b32_dpp v10, v8 row_ror:8 row_mask:0xf bank_mask:0xf
	s_waitcnt lgkmcnt(0)
	v_add_f32_e32 v8, v8, v10
	s_nop 1
	v_mov_b32_dpp v10, v8 row_shl:4 row_mask:0xf bank_mask:0x5
	v_mov_b32_dpp v10, v8 row_shr:4 row_mask:0xf bank_mask:0xa
	s_waitcnt lgkmcnt(0)
	v_add_f32_e32 v8, v8, v10
	s_nop 1
	v_mov_b32_dpp v10, v8 quad_perm:[2,3,0,1] row_mask:0xf bank_mask:0xf
	s_waitcnt lgkmcnt(0)
	v_add_f32_e32 v8, v8, v10
	s_nop 1
	v_mov_b32_dpp v10, v8 quad_perm:[1,0,3,2] row_mask:0xf bank_mask:0xf
	s_waitcnt lgkmcnt(0)
	v_add_f32_e32 v8, v8, v10
	v_fmamk_f32 v8, v8, 0x3a800000, v250
	v_mul_f32_e32 v10, 0x4b800000, v8
	v_cmp_gt_f32_e32 vcc, s81, v8
	s_nop 1
	v_cndmask_b32_e32 v8, v8, v10, vcc
	v_rsq_f32_e32 v8, v8
	s_nop 0
	v_mul_f32_e32 v10, 0x45800000, v8
	v_cndmask_b32_e32 v8, v8, v10, vcc
	s_and_saveexec_b64 s[10:11], s[0:1]
	s_cbranch_execz .LBB0_178
	v_ashrrev_i32_e32 v51, 31, v50
	v_readlane_b32 s12, v254, 29
	v_lshlrev_b64 v[10:11], 2, v[50:51]
	v_readlane_b32 s13, v254, 30
	v_mul_f32_e32 v9, 0x3a800000, v9
	s_nop 0
	v_lshl_add_u64 v[12:13], s[12:13], 0, v[10:11]
	v_lshl_add_u64 v[10:11], s[78:79], 0, v[10:11]
	v_add_co_u32_e32 v10, vcc, 0xdf000, v10
	global_store_dword v[12:13], v9, off
	s_nop 0
	v_addc_co_u32_e32 v11, vcc, 0, v11, vcc
	global_store_dword v[10:11], v8, off offset:4
	s_branch .LBB0_178

; DI float shx(float v, int m, int lane) { return __builtin_bit_cast(float, __builtin_amdgcn_ds_bpermute((lane ^ m) << 2, __builtin_bit_cast(int, v))); }
; template <int PR>
; DI void prep_rows(const int lane, const Params& p, int l, int which, int rbeg, int rend, int gw, int nw) {
;     ...
;                 const bf16_t* src = P_WSB(OFF_Z) + (size_t)r2 * 1024;
; #pragma unroll
;                 for (int i = 0; i < 4; i += 2) { const u32x4 zz = *(const u32x4*)(src + PCOL(i)); const u32x2 zl = {zz[0], zz[1]}, zh = {zz[2], zz[3]}; v[rr][i] = unpk4(zl); v[rr][i + 1] = unpk4(zh); }
;     ...
;             for (int rr = 0; rr < PR; ++rr) { float s = 0.f;
; #pragma unroll
;                 for (int i = 0; i < 4; ++i) s += v[rr][i][0] + v[rr][i][1] + v[rr][i][2] + v[rr][i][3];
;                 sm[rr] = s; }
; #pragma unroll
;             for (int o = 32; o >= 1; o >>= 1)
; #pragma unroll
;                 for (int rr = 0; rr < PR; ++rr) sm[rr] += shx(sm[rr], o, lane);
.LBB0_191:
	v_add_co_u32_e32 v0, vcc, 0xf86bf000, v24
	s_nop 1
	v_addc_co_u32_e32 v1, vcc, -1, v25, vcc
	global_load_dwordx4 v[12:15], v[0:1], off offset:-3072
	global_load_dwordx4 v[36:39], v[0:1], off offset:-2048
	global_load_dwordx4 v[46:49], v[0:1], off offset:-1024
	global_load_dwordx4 v[50:53], v[0:1], off
	v_add_co_u32_e32 v0, vcc, 0xf86c0000, v24
	s_waitcnt vmcnt(0)
	v_lshlrev_b32_e32 v29, 16, v12
	v_addc_co_u32_e32 v1, vcc, -1, v25, vcc
	global_load_dwordx4 v[66:69], v[0:1], off offset:-3072
	global_load_dwordx4 v[8:11], v[0:1], off offset:-2048
	global_load_dwordx4 v[4:7], v[0:1], off offset:-1024
	s_nop 0
	global_load_dwordx4 v[0:3], v[0:1], off
	v_lshlrev_b32_e32 v28, 16, v14
	v_and_b32_e32 v59, 0xffff0000, v12
	v_and_b32_e32 v58, 0xffff0000, v14
	v_lshlrev_b32_e32 v33, 16, v13
	v_lshlrev_b32_e32 v32, 16, v15
	v_and_b32_e32 v35, 0xffff0000, v13
	v_pk_add_f32 v[12:13], v[28:29], v[58:59]
	v_and_b32_e32 v34, 0xffff0000, v15
	v_pk_add_f32 v[12:13], v[12:13], v[32:33]
	v_and_b32_e32 v61, 0xffff0000, v36
	v_pk_add_f32 v[12:13], v[12:13], v[34:35]
	v_and_b32_e32 v60, 0xffff0000, v38
	v_add_f32_e32 v13, 0, v13
	v_add_f32_e32 v17, v12, v13
	v_lshlrev_b32_e32 v13, 16, v36
	v_lshlrev_b32_e32 v12, 16, v38
	v_lshlrev_b32_e32 v15, 16, v37
	v_lshlrev_b32_e32 v14, 16, v39
	v_and_b32_e32 v31, 0xffff0000, v37
	v_pk_add_f32 v[36:37], v[12:13], v[60:61]
	v_and_b32_e32 v30, 0xffff0000, v39
	v_pk_add_f32 v[36:37], v[36:37], v[14:15]
	v_lshlrev_b32_e32 v41, 16, v46
	v_pk_add_f32 v[36:37], v[36:37], v[30:31]
	v_lshlrev_b32_e32 v40, 16, v48
	v_add_f32_e32 v17, v37, v17
	v_and_b32_e32 v63, 0xffff0000, v46
	v_and_b32_e32 v62, 0xffff0000, v48
	v_add_f32_e32 v17, v36, v17
	v_lshlrev_b32_e32 v45, 16, v47
	v_lshlrev_b32_e32 v44, 16, v49
	v_pk_add_f32 v[36:37], v[40:41], v[62:63]
	v_and_b32_e32 v47, 0xffff0000, v47
	v_and_b32_e32 v46, 0xffff0000, v49
	v_pk_add_f32 v[36:37], v[36:37], v[44:45]
	v_and_b32_e32 v65, 0xffff0000, v50
	v_pk_add_f32 v[36:37], v[36:37], v[46:47]
	v_and_b32_e32 v64, 0xffff0000, v52
	v_add_f32_e32 v23, 0, v37
	v_add_f32_e32 v23, v36, v23
	v_lshlrev_b32_e32 v37, 16, v50
	v_lshlrev_b32_e32 v36, 16, v52
	v_lshlrev_b32_e32 v39, 16, v51
	v_lshlrev_b32_e32 v38, 16, v53
	v_pk_add_f32 v[48:49], v[36:37], v[64:65]
	v_and_b32_e32 v43, 0xffff0000, v51
	v_and_b32_e32 v42, 0xffff0000, v53
	v_pk_add_f32 v[48:49], v[48:49], v[38:39]
	s_waitcnt vmcnt(0)
	v_lshlrev_b32_e32 v53, 16, v66
	v_pk_add_f32 v[48:49], v[48:49], v[42:43]
	v_lshlrev_b32_e32 v52, 16, v68
	v_add_f32_e32 v23, v49, v23
	v_and_b32_e32 v71, 0xffff0000, v66
	v_and_b32_e32 v70, 0xffff0000, v68
	v_add_f32_e32 v23, v48, v23
	v_lshlrev_b32_e32 v55, 16, v67
	v_lshlrev_b32_e32 v54, 16, v69
	v_pk_add_f32 v[48:49], v[52:53], v[70:71]
	v_and_b32_e32 v57, 0xffff0000, v67
	v_and_b32_e32 v56, 0xffff0000, v69
	v_pk_add_f32 v[48:49], v[48:49], v[54:55]
	v_and_b32_e32 v73, 0xffff0000, v8
	v_pk_add_f32 v[48:49], v[48:49], v[56:57]
	v_and_b32_e32 v72, 0xffff0000, v10
	v_add_f32_e32 v27, 0, v49
	v_add_f32_e32 v27, v48, v27
	v_lshlrev_b32_e32 v49, 16, v8
	v_lshlrev_b32_e32 v48, 16, v10
	v_lshlrev_b32_e32 v51, 16, v9
	v_lshlrev_b32_e32 v50, 16, v11
	v_and_b32_e32 v8, 0xffff0000, v11
	v_pk_add_f32 v[10:11], v[48:49], v[72:73]
	v_and_b32_e32 v9, 0xffff0000, v9
	v_pk_add_f32 v[10:11], v[10:11], v[50:51]
	v_and_b32_e32 v75, 0xffff0000, v4
	v_pk_add_f32 v[10:11], v[10:11], v[8:9]
	v_and_b32_e32 v74, 0xffff0000, v6
	v_add_f32_e32 v11, v11, v27
	v_add_f32_e32 v27, v10, v11
	v_lshlrev_b32_e32 v11, 16, v4
	v_lshlrev_b32_e32 v10, 16, v6
	v_lshlrev_b32_e32 v67, 16, v5
	v_lshlrev_b32_e32 v66, 16, v7
	v_and_b32_e32 v69, 0xffff0000, v5
	v_pk_add_f32 v[4:5], v[10:11], v[74:75]
	v_and_b32_e32 v68, 0xffff0000, v7
	v_pk_add_f32 v[4:5], v[4:5], v[66:67]
	v_and_b32_e32 v77, 0xffff0000, v0
	v_pk_add_f32 v[4:5], v[4:5], v[68:69]
	v_and_b32_e32 v76, 0xffff0000, v2
	v_add_f32_e32 v5, 0, v5
	v_add_f32_e32 v78, v4, v5
	v_lshlrev_b32_e32 v5, 16, v0
	v_lshlrev_b32_e32 v4, 16, v2
	v_lshlrev_b32_e32 v7, 16, v1
	v_lshlrev_b32_e32 v6, 16, v3
	v_and_b32_e32 v0, 0xffff0000, v3
	v_pk_add_f32 v[2:3], v[4:5], v[76:77]
	v_and_b32_e32 v1, 0xffff0000, v1
	v_pk_add_f32 v[2:3], v[2:3], v[6:7]
	s_nop 0
	v_pk_add_f32 v[2:3], v[2:3], v[0:1]
	s_nop 0
	v_add_f32_e32 v3, v3, v78
	v_add_f32_e32 v2, v2, v3
	v_mov_b32_e32 v240, v17
	v_mov_b32_e32 v3, v17
	s_nop 1
	v_permlane32_swap_b32_e32 v240, v3
	s_nop 1
	v_mov_b32_dpp v3, v240 quad_perm:[0,1,2,3] row_mask:0xc bank_mask:0xf
	s_waitcnt lgkmcnt(0)
	v_add_f32_e32 v3, v17, v3
	v_mov_b32_e32 v240, v23
	v_mov_b32_e32 v17, v23
	s_nop 1
	v_permlane32_swap_b32_e32 v240, v17
	s_nop 1
	v_mov_b32_dpp v17, v240 quad_perm:[0,1,2,3] row_mask:0xc bank_mask:0xf
	s_waitcnt lgkmcnt(0)
	v_add_f32_e32 v17, v23, v17
	v_mov_b32_e32 v240, v27
	v_mov_b32_e32 v23, v27
	s_nop 1
	v_permlane32_swap_b32_e32 v240, v23
	s_nop 1
	v_mov_b32_dpp v23, v240 quad_perm:[0,1,2,3] row_mask:0xc bank_mask:0xf
	s_waitcnt lgkmcnt(0)
	v_add_f32_e32 v23, v27, v23
	v_mov_b32_e32 v240, v2
	v_mov_b32_e32 v27, v2
	s_nop 1
	v_permlane32_swap_b32_e32 v240, v27
	s_nop 1
	v_mov_b32_dpp v27, v240 quad_perm:[0,1,2,3] row_mask:0xc bank_mask:0xf
	s_waitcnt lgkmcnt(0)
	v_add_f32_e32 v2, v2, v27
	v_mov_b32_e32 v240, v3
	v_mov_b32_e32 v27, v3
	s_nop 1
	v_permlane16_swap_b32_e32 v240, v27
	s_nop 1
	v_mov_b32_dpp v27, v240 quad_perm:[0,1,2,3] row_mask:0xa bank_mask:0xf
	s_waitcnt lgkmcnt(0)
	v_add_f32_e32 v3, v3, v27
	v_mov_b32_e32 v240, v17
	v_mov_b32_e32 v27, v17
	s_nop 1
	v_permlane16_swap_b32_e32 v240, v27
	s_nop 1
	v_mov_b32_dpp v27, v240 quad_perm:[0,1,2,3] row_mask:0xa bank_mask:0xf
	s_waitcnt lgkmcnt(0)
; DI float shx(float v, int m, int lane) { return __builtin_bit_cast(float, __builtin_amdgcn_ds_bpermute((lane ^ m) << 2, __builtin_bit_cast(int, v))); }
; template <int PR>
; DI void prep_rows(const int lane, const Params& p, int l, int which, int rbeg, int rend, int gw, int nw) {
;     ...
;             for (int o = 32; o >= 1; o >>= 1)
; #pragma unroll
;                 for (int rr = 0; rr < PR; ++rr) sm[rr] += shx(sm[rr], o, lane);
; #pragma unroll
;             for (int rr = 0; rr < PR; ++rr) { const float mean = sm[rr] * (1.f / 1024.f); sm[rr] = mean; float q = 0.f;
; #pragma unroll
;                 for (int i = 0; i < 4; ++i) { v[rr][i] -= mean; q += v[rr][i][0] * v[rr][i][0] + v[rr][i][1] * v[rr][i][1] + v[rr][i][2] * v[rr][i][2] + v[rr][i][3] * v[rr][i][3]; }
;                 sq[rr] = q; }
	v_add_f32_e32 v17, v17, v27
	v_mov_b32_e32 v240, v23
	v_mov_b32_e32 v27, v23
	s_nop 1
	v_permlane16_swap_b32_e32 v240, v27
	s_nop 1
	v_mov_b32_dpp v27, v240 quad_perm:[0,1,2,3] row_mask:0xa bank_mask:0xf
	s_waitcnt lgkmcnt(0)
	v_add_f32_e32 v23, v23, v27
	v_mov_b32_e32 v240, v2
	v_mov_b32_e32 v27, v2
	s_nop 1
	v_permlane16_swap_b32_e32 v240, v27
	s_nop 1
	v_mov_b32_dpp v27, v240 quad_perm:[0,1,2,3] row_mask:0xa bank_mask:0xf
	s_waitcnt lgkmcnt(0)
	v_add_f32_e32 v2, v2, v27
	s_nop 1
	v_mov_b32_dpp v27, v3 row_ror:8 row_mask:0xf bank_mask:0xf
	s_waitcnt lgkmcnt(0)
	v_add_f32_e32 v3, v3, v27
	s_nop 1
	v_mov_b32_dpp v27, v17 row_ror:8 row_mask:0xf bank_mask:0xf
	s_waitcnt lgkmcnt(0)
	v_add_f32_e32 v17, v17, v27
	s_nop 1
	v_mov_b32_dpp v27, v23 row_ror:8 row_mask:0xf bank_mask:0xf
	s_waitcnt lgkmcnt(0)
	v_add_f32_e32 v23, v23, v27
	s_nop 1
	v_mov_b32_dpp v27, v2 row_ror:8 row_mask:0xf bank_mask:0xf
	s_waitcnt lgkmcnt(0)
	v_add_f32_e32 v2, v2, v27
	s_nop 1
	v_mov_b32_dpp v27, v3 row_shl:4 row_mask:0xf bank_mask:0x5
	v_mov_b32_dpp v27, v3 row_shr:4 row_mask:0xf bank_mask:0xa
	s_waitcnt lgkmcnt(0)
	v_add_f32_e32 v3, v3, v27
	s_nop 1
	v_mov_b32_dpp v27, v17 row_shl:4 row_mask:0xf bank_mask:0x5
	v_mov_b32_dpp v27, v17 row_shr:4 row_mask:0xf bank_mask:0xa
	s_waitcnt lgkmcnt(0)
	v_add_f32_e32 v17, v17, v27
	s_nop 1
	v_mov_b32_dpp v27, v23 row_shl:4 row_mask:0xf bank_mask:0x5
	v_mov_b32_dpp v27, v23 row_shr:4 row_mask:0xf bank_mask:0xa
	s_waitcnt lgkmcnt(0)
	v_add_f32_e32 v23, v23, v27
	s_nop 1
	v_mov_b32_dpp v27, v2 row_shl:4 row_mask:0xf bank_mask:0x5
	v_mov_b32_dpp v27, v2 row_shr:4 row_mask:0xf bank_mask:0xa
	s_waitcnt lgkmcnt(0)
	v_add_f32_e32 v2, v2, v27
	s_nop 1
	v_mov_b32_dpp v27, v3 quad_perm:[2,3,0,1] row_mask:0xf bank_mask:0xf
	s_waitcnt lgkmcnt(0)
	v_add_f32_e32 v3, v3, v27
	s_nop 1
	v_mov_b32_dpp v27, v17 quad_perm:[2,3,0,1] row_mask:0xf bank_mask:0xf
	s_waitcnt lgkmcnt(0)
	v_add_f32_e32 v17, v17, v27
	s_nop 1
	v_mov_b32_dpp v27, v23 quad_perm:[2,3,0,1] row_mask:0xf bank_mask:0xf
	s_waitcnt lgkmcnt(0)
	v_add_f32_e32 v23, v23, v27
	s_nop 1
	v_mov_b32_dpp v27, v2 quad_perm:[2,3,0,1] row_mask:0xf bank_mask:0xf
	s_waitcnt lgkmcnt(0)
	v_add_f32_e32 v2, v2, v27
	s_nop 1
	v_mov_b32_dpp v27, v3 quad_perm:[1,0,3,2] row_mask:0xf bank_mask:0xf
	s_waitcnt lgkmcnt(0)
	v_add_f32_e32 v78, v3, v27
	s_nop 1
	v_mov_b32_dpp v3, v17 quad_perm:[1,0,3,2] row_mask:0xf bank_mask:0xf
	v_fmac_f32_e32 v59, 0xba800000, v78
	v_fmac_f32_e32 v58, 0xba800000, v78
	v_fmac_f32_e32 v29, 0xba800000, v78
	v_fmac_f32_e32 v28, 0xba800000, v78
	s_waitcnt lgkmcnt(0)
	v_add_f32_e32 v27, v17, v3
	s_nop 1
	v_mov_b32_dpp v3, v23 quad_perm:[1,0,3,2] row_mask:0xf bank_mask:0xf
	v_fmac_f32_e32 v63, 0xba800000, v27
	v_fmac_f32_e32 v62, 0xba800000, v27
	v_fmac_f32_e32 v41, 0xba800000, v27
	v_fmac_f32_e32 v40, 0xba800000, v27
	s_waitcnt lgkmcnt(0)
	v_add_f32_e32 v17, v23, v3
	v_mul_f32_e32 v23, v63, v63
	v_mul_f32_e32 v79, v62, v62
	v_fmac_f32_e32 v45, 0xba800000, v27
	v_fmac_f32_e32 v23, v41, v41
	v_fmac_f32_e32 v44, 0xba800000, v27
	v_fmac_f32_e32 v79, v40, v40
	v_fmac_f32_e32 v47, 0xba800000, v27
	v_fmac_f32_e32 v23, v45, v45
	v_fmac_f32_e32 v46, 0xba800000, v27
	v_fmac_f32_e32 v79, v44, v44
	v_fmac_f32_e32 v23, v47, v47
	v_fmac_f32_e32 v79, v46, v46
	v_fmac_f32_e32 v65, 0xba800000, v27
	v_add_f32_e32 v23, v23, v79
	v_fmac_f32_e32 v37, 0xba800000, v27
	v_mul_f32_e32 v79, v65, v65
	v_fmac_f32_e32 v39, 0xba800000, v27
	v_fmac_f32_e32 v79, v37, v37
	v_fmac_f32_e32 v43, 0xba800000, v27
	v_fmac_f32_e32 v79, v39, v39
	s_nop 1
	v_mov_b32_dpp v3, v2 quad_perm:[1,0,3,2] row_mask:0xf bank_mask:0xf
	v_mov_b32_e32 v82, v59
	v_mov_b32_e32 v83, v58
	v_fmac_f32_e32 v79, v43, v43
	v_fmac_f32_e32 v64, 0xba800000, v27
	v_fmac_f32_e32 v33, 0xba800000, v78
	v_fmac_f32_e32 v32, 0xba800000, v78
	v_mov_b32_e32 v80, v29
	v_mov_b32_e32 v81, v28
	v_pk_mul_f32 v[82:83], v[82:83], v[82:83]
	v_add_f32_e32 v23, v79, v23
	v_fmac_f32_e32 v36, 0xba800000, v27
	v_mul_f32_e32 v79, v64, v64
	v_fmac_f32_e32 v35, 0xba800000, v78
	v_fmac_f32_e32 v34, 0xba800000, v78
	v_pk_fma_f32 v[80:81], v[80:81], v[80:81], v[82:83]
	v_mov_b32_e32 v82, v33
	v_mov_b32_e32 v83, v32
	v_fmac_f32_e32 v38, 0xba800000, v27
	v_fmac_f32_e32 v79, v36, v36
	v_pk_fma_f32 v[80:81], v[82:83], v[82:83], v[80:81]
	v_mov_b32_e32 v82, v35
	v_mov_b32_e32 v83, v34
	v_fmac_f32_e32 v42, 0xba800000, v27
	v_fmac_f32_e32 v79, v38, v38
	v_pk_fma_f32 v[80:81], v[82:83], v[82:83], v[80:81]
	v_fmac_f32_e32 v79, v42, v42
	v_fmac_f32_e32 v71, 0xba800000, v17
	v_fmac_f32_e32 v70, 0xba800000, v17
	s_waitcnt lgkmcnt(0)
; DI float shx(float v, int m, int lane) { return __builtin_bit_cast(float, __builtin_amdgcn_ds_bpermute((lane ^ m) << 2, __builtin_bit_cast(int, v))); }
; template <int PR>
; DI void prep_rows(const int lane, const Params& p, int l, int which, int rbeg, int rend, int gw, int nw) {
;     ...
;             for (int rr = 0; rr < PR; ++rr) { const float mean = sm[rr] * (1.f / 1024.f); sm[rr] = mean; float q = 0.f;
; #pragma unroll
;                 for (int i = 0; i < 4; ++i) { v[rr][i] -= mean; q += v[rr][i][0] * v[rr][i][0] + v[rr][i][1] * v[rr][i][1] + v[rr][i][2] * v[rr][i][2] + v[rr][i][3] * v[rr][i][3]; }
;                 sq[rr] = q; }
; #pragma unroll
;             for (int o = 32; o >= 1; o >>= 1)
; #pragma unroll
;                 for (int rr = 0; rr < PR; ++rr) sq[rr] += shx(sq[rr], o, lane);
	v_add_f32_e32 v3, v2, v3
	v_add_f32_e32 v2, v80, v81
	v_add_f32_e32 v23, v79, v23
	v_fmac_f32_e32 v53, 0xba800000, v17
	v_mul_f32_e32 v79, v71, v71
	v_fmac_f32_e32 v52, 0xba800000, v17
	v_mul_f32_e32 v80, v70, v70
	v_fmac_f32_e32 v55, 0xba800000, v17
	v_fmac_f32_e32 v79, v53, v53
	v_fmac_f32_e32 v54, 0xba800000, v17
	v_fmac_f32_e32 v80, v52, v52
	v_fmac_f32_e32 v57, 0xba800000, v17
	v_fmac_f32_e32 v79, v55, v55
	v_fmac_f32_e32 v56, 0xba800000, v17
	v_fmac_f32_e32 v80, v54, v54
	v_fmac_f32_e32 v79, v57, v57
	v_fmac_f32_e32 v80, v56, v56
	v_fmac_f32_e32 v73, 0xba800000, v17
	v_add_f32_e32 v79, v79, v80
	v_fmac_f32_e32 v49, 0xba800000, v17
	v_mul_f32_e32 v80, v73, v73
	v_fmac_f32_e32 v51, 0xba800000, v17
	v_fmac_f32_e32 v80, v49, v49
	v_fmac_f32_e32 v9, 0xba800000, v17
	v_fmac_f32_e32 v80, v51, v51
	v_fmac_f32_e32 v80, v9, v9
	v_fmac_f32_e32 v72, 0xba800000, v17
	v_add_f32_e32 v79, v80, v79
	v_fmac_f32_e32 v48, 0xba800000, v17
	v_mul_f32_e32 v80, v72, v72
	v_fmac_f32_e32 v50, 0xba800000, v17
	v_fmac_f32_e32 v80, v48, v48
	v_fmac_f32_e32 v8, 0xba800000, v17
	v_fmac_f32_e32 v80, v50, v50
	v_fmac_f32_e32 v80, v8, v8
	v_fmac_f32_e32 v75, 0xba800000, v3
	v_fmac_f32_e32 v74, 0xba800000, v3
	v_add_f32_e32 v79, v80, v79
	v_fmac_f32_e32 v11, 0xba800000, v3
	v_mul_f32_e32 v80, v75, v75
	v_fmac_f32_e32 v10, 0xba800000, v3
	v_mul_f32_e32 v81, v74, v74
	v_fmac_f32_e32 v67, 0xba800000, v3
	v_fmac_f32_e32 v80, v11, v11
	v_fmac_f32_e32 v66, 0xba800000, v3
	v_fmac_f32_e32 v81, v10, v10
	v_fmac_f32_e32 v69, 0xba800000, v3
	v_fmac_f32_e32 v80, v67, v67
	v_fmac_f32_e32 v68, 0xba800000, v3
	v_fmac_f32_e32 v81, v66, v66
	v_fmac_f32_e32 v80, v69, v69
	v_fmac_f32_e32 v81, v68, v68
	v_fmac_f32_e32 v77, 0xba800000, v3
	v_add_f32_e32 v80, v80, v81
	v_fmac_f32_e32 v5, 0xba800000, v3
	v_mul_f32_e32 v81, v77, v77
	v_fmac_f32_e32 v61, 0xba800000, v78
	v_fmac_f32_e32 v60, 0xba800000, v78
	v_fmac_f32_e32 v7, 0xba800000, v3
	v_fmac_f32_e32 v81, v5, v5
	v_fmac_f32_e32 v13, 0xba800000, v78
	v_fmac_f32_e32 v12, 0xba800000, v78
	v_pk_mul_f32 v[82:83], v[60:61], v[60:61]
	v_fmac_f32_e32 v1, 0xba800000, v3
	v_fmac_f32_e32 v81, v7, v7
	v_fmac_f32_e32 v15, 0xba800000, v78
	v_fmac_f32_e32 v14, 0xba800000, v78
	v_pk_fma_f32 v[82:83], v[12:13], v[12:13], v[82:83]
	v_fmac_f32_e32 v81, v1, v1
	v_fmac_f32_e32 v76, 0xba800000, v3
	v_fmac_f32_e32 v31, 0xba800000, v78
	v_fmac_f32_e32 v30, 0xba800000, v78
	v_pk_fma_f32 v[82:83], v[14:15], v[14:15], v[82:83]
	v_add_f32_e32 v80, v81, v80
	v_fmac_f32_e32 v4, 0xba800000, v3
	v_mul_f32_e32 v81, v76, v76
	v_pk_fma_f32 v[82:83], v[30:31], v[30:31], v[82:83]
	v_fmac_f32_e32 v6, 0xba800000, v3
	v_fmac_f32_e32 v81, v4, v4
	v_add_f32_e32 v2, v83, v2
	v_fmac_f32_e32 v0, 0xba800000, v3
	v_fmac_f32_e32 v81, v6, v6
	v_add_f32_e32 v2, v82, v2
	v_fmac_f32_e32 v81, v0, v0
	v_add_f32_e32 v80, v81, v80
	v_mov_b32_e32 v240, v2
	v_mov_b32_e32 v81, v2
	s_nop 1
	v_permlane32_swap_b32_e32 v240, v81
	s_nop 1
	v_mov_b32_dpp v81, v240 quad_perm:[0,1,2,3] row_mask:0xc bank_mask:0xf
	s_waitcnt lgkmcnt(0)
	v_add_f32_e32 v2, v2, v81
	v_mov_b32_e32 v240, v23
	v_mov_b32_e32 v81, v23
	s_nop 1
	v_permlane32_swap_b32_e32 v240, v81
	s_nop 1
	v_mov_b32_dpp v81, v240 quad_perm:[0,1,2,3] row_mask:0xc bank_mask:0xf
	s_waitcnt lgkmcnt(0)
	v_add_f32_e32 v23, v23, v81
	v_mov_b32_e32 v240, v79
	v_mov_b32_e32 v81, v79
	s_nop 1
	v_permlane32_swap_b32_e32 v240, v81
	s_nop 1
	v_mov_b32_dpp v81, v240 quad_perm:[0,1,2,3] row_mask:0xc bank_mask:0xf
	s_waitcnt lgkmcnt(0)
	v_add_f32_e32 v79, v79, v81
	v_mov_b32_e32 v240, v80
	v_mov_b32_e32 v81, v80
	s_nop 1
	v_permlane32_swap_b32_e32 v240, v81
	s_nop 1
	v_mov_b32_dpp v81, v240 quad_perm:[0,1,2,3] row_mask:0xc bank_mask:0xf
	s_waitcnt lgkmcnt(0)
; DI float shx(float v, int m, int lane) { return __builtin_bit_cast(float, __builtin_amdgcn_ds_bpermute((lane ^ m) << 2, __builtin_bit_cast(int, v))); }
; template <int PR>
; DI void prep_rows(const int lane, const Params& p, int l, int which, int rbeg, int rend, int gw, int nw) {
;     ...
;             for (int o = 32; o >= 1; o >>= 1)
; #pragma unroll
;                 for (int rr = 0; rr < PR; ++rr) sq[rr] += shx(sq[rr], o, lane);
; #pragma unroll
;             for (int rr = 0; rr < PR; ++rr) { sq[rr] = rsqrtf(sq[rr] * (1.f / 1024.f) + LN_EPS);
;                 if (which != 2 && lane == 0) { P_WSF(OFF_STATS)[2 * (row + rr)] = sm[rr]; P_WSF(OFF_STATS)[2 * (row + rr) + 1] = sq[rr]; } }
	v_add_f32_e32 v80, v80, v81
	v_mov_b32_e32 v240, v2
	v_mov_b32_e32 v81, v2
	s_nop 1
	v_permlane16_swap_b32_e32 v240, v81
	s_nop 1
	v_mov_b32_dpp v81, v240 quad_perm:[0,1,2,3] row_mask:0xa bank_mask:0xf
	s_waitcnt lgkmcnt(0)
	v_add_f32_e32 v2, v2, v81
	v_mov_b32_e32 v240, v23
	v_mov_b32_e32 v81, v23
	s_nop 1
	v_permlane16_swap_b32_e32 v240, v81
	s_nop 1
	v_mov_b32_dpp v81, v240 quad_perm:[0,1,2,3] row_mask:0xa bank_mask:0xf
	s_waitcnt lgkmcnt(0)
	v_add_f32_e32 v23, v23, v81
	v_mov_b32_e32 v240, v79
	v_mov_b32_e32 v81, v79
	s_nop 1
	v_permlane16_swap_b32_e32 v240, v81
	s_nop 1
	v_mov_b32_dpp v81, v240 quad_perm:[0,1,2,3] row_mask:0xa bank_mask:0xf
	s_waitcnt lgkmcnt(0)
	v_add_f32_e32 v79, v79, v81
	v_mov_b32_e32 v240, v80
	v_mov_b32_e32 v81, v80
	s_nop 1
	v_permlane16_swap_b32_e32 v240, v81
	s_nop 1
	v_mov_b32_dpp v81, v240 quad_perm:[0,1,2,3] row_mask:0xa bank_mask:0xf
	s_waitcnt lgkmcnt(0)
	v_add_f32_e32 v80, v80, v81
	s_nop 1
	v_mov_b32_dpp v81, v2 row_ror:8 row_mask:0xf bank_mask:0xf
	s_waitcnt lgkmcnt(0)
	v_add_f32_e32 v2, v2, v81
	s_nop 1
	v_mov_b32_dpp v81, v23 row_ror:8 row_mask:0xf bank_mask:0xf
	s_waitcnt lgkmcnt(0)
	v_add_f32_e32 v23, v23, v81
	s_nop 1
	v_mov_b32_dpp v81, v79 row_ror:8 row_mask:0xf bank_mask:0xf
	s_waitcnt lgkmcnt(0)
	v_add_f32_e32 v79, v79, v81
	s_nop 1
	v_mov_b32_dpp v81, v80 row_ror:8 row_mask:0xf bank_mask:0xf
	s_waitcnt lgkmcnt(0)
	v_add_f32_e32 v80, v80, v81
	s_nop 1
	v_mov_b32_dpp v81, v2 row_shl:4 row_mask:0xf bank_mask:0x5
	v_mov_b32_dpp v81, v2 row_shr:4 row_mask:0xf bank_mask:0xa
	s_waitcnt lgkmcnt(0)
	v_add_f32_e32 v2, v2, v81
	s_nop 1
	v_mov_b32_dpp v81, v23 row_shl:4 row_mask:0xf bank_mask:0x5
	v_mov_b32_dpp v81, v23 row_shr:4 row_mask:0xf bank_mask:0xa
	s_waitcnt lgkmcnt(0)
	v_add_f32_e32 v23, v23, v81
	s_nop 1
	v_mov_b32_dpp v81, v79 row_shl:4 row_mask:0xf bank_mask:0x5
	v_mov_b32_dpp v81, v79 row_shr:4 row_mask:0xf bank_mask:0xa
	s_waitcnt lgkmcnt(0)
	v_add_f32_e32 v79, v79, v81
	s_nop 1
	v_mov_b32_dpp v81, v80 row_shl:4 row_mask:0xf bank_mask:0x5
	v_mov_b32_dpp v81, v80 row_shr:4 row_mask:0xf bank_mask:0xa
	s_waitcnt lgkmcnt(0)
	v_add_f32_e32 v80, v80, v81
	s_nop 1
	v_mov_b32_dpp v81, v2 quad_perm:[2,3,0,1] row_mask:0xf bank_mask:0xf
	s_waitcnt lgkmcnt(0)
	v_add_f32_e32 v2, v2, v81
	s_nop 1
	v_mov_b32_dpp v81, v23 quad_perm:[2,3,0,1] row_mask:0xf bank_mask:0xf
	s_waitcnt lgkmcnt(0)
	v_add_f32_e32 v83, v23, v81
	s_nop 1
	v_mov_b32_dpp v23, v79 quad_perm:[2,3,0,1] row_mask:0xf bank_mask:0xf
	s_nop 1
	v_mov_b32_dpp v84, v83 quad_perm:[1,0,3,2] row_mask:0xf bank_mask:0xf
	s_waitcnt lgkmcnt(1)
	v_add_f32_e32 v81, v79, v23
	s_nop 1
	v_mov_b32_dpp v23, v80 quad_perm:[2,3,0,1] row_mask:0xf bank_mask:0xf
	s_nop 1
	v_mov_b32_dpp v82, v81 quad_perm:[1,0,3,2] row_mask:0xf bank_mask:0xf
	s_waitcnt lgkmcnt(1)
	v_add_f32_e32 v79, v80, v23
	s_nop 1
	v_mov_b32_dpp v23, v2 quad_perm:[1,0,3,2] row_mask:0xf bank_mask:0xf
	s_nop 1
	v_mov_b32_dpp v80, v79 quad_perm:[1,0,3,2] row_mask:0xf bank_mask:0xf
	s_waitcnt lgkmcnt(1)
	v_add_f32_e32 v2, v2, v23
	v_fmamk_f32 v2, v2, 0x3a800000, v250
	v_cmp_gt_f32_e32 vcc, s81, v2
	v_mul_f32_e32 v23, 0x4b800000, v2
	s_nop 0
	v_cndmask_b32_e32 v2, v2, v23, vcc
	v_rsq_f32_e32 v2, v2
	s_nop 0
	v_mul_f32_e32 v23, 0x45800000, v2
	v_cndmask_b32_e32 v2, v2, v23, vcc
	v_ashrrev_i32_e32 v23, 31, v22
	s_and_saveexec_b64 s[8:9], s[0:1]
	s_cbranch_execz .LBB0_193
	v_readlane_b32 s2, v254, 29
	v_lshlrev_b64 v[86:87], 2, v[22:23]
	v_readlane_b32 s3, v254, 30
	v_mul_f32_e32 v78, 0x3a800000, v78
	v_lshl_add_u64 v[88:89], s[78:79], 0, v[86:87]
	v_lshl_add_u64 v[86:87], s[2:3], 0, v[86:87]
	global_store_dword v[86:87], v78, off
	v_add_co_u32_e32 v86, vcc, 0xdf000, v88
	s_nop 1
	v_addc_co_u32_e32 v87, vcc, 0, v89, vcc
	global_store_dword v[86:87], v2, off offset:4

; DI float shx(float v, int m, int lane) { return __builtin_bit_cast(float, __builtin_amdgcn_ds_bpermute((lane ^ m) << 2, __builtin_bit_cast(int, v))); }
; template <int PR>
; DI void prep_rows(const int lane, const Params& p, int l, int which, int rbeg, int rend, int gw, int nw) {
;     ...
;             for (int rr = 0; rr < PR; ++rr) { float s = 0.f;
; #pragma unroll
;                 for (int i = 0; i < 4; ++i) s += v[rr][i][0] + v[rr][i][1] + v[rr][i][2] + v[rr][i][3];
;                 sm[rr] = s; }
; #pragma unroll
;             for (int o = 32; o >= 1; o >>= 1)
; #pragma unroll
;                 for (int rr = 0; rr < PR; ++rr) sm[rr] += shx(sm[rr], o, lane);
; #pragma unroll
;             for (int rr = 0; rr < PR; ++rr) { const float mean = sm[rr] * (1.f / 1024.f); sm[rr] = mean; float q = 0.f;
; #pragma unroll
;                 for (int i = 0; i < 4; ++i) { v[rr][i] -= mean; q += v[rr][i][0] * v[rr][i][0] + v[rr][i][1] * v[rr][i][1] + v[rr][i][2] * v[rr][i][2] + v[rr][i][3] * v[rr][i][3]; }
;                 sq[rr] = q; }
; #pragma unroll
;             for (int o = 32; o >= 1; o >>= 1)
; #pragma unroll
;                 for (int rr = 0; rr < PR; ++rr) sq[rr] += shx(sq[rr], o, lane);
; #pragma unroll
;             for (int rr = 0; rr < PR; ++rr) { sq[rr] = rsqrtf(sq[rr] * (1.f / 1024.f) + LN_EPS);
;                 if (which != 2 && lane == 0) { P_WSF(OFF_STATS)[2 * (row + rr)] = sm[rr]; P_WSF(OFF_STATS)[2 * (row + rr) + 1] = sq[rr]; } }
.LBB0_514:
	s_waitcnt vmcnt(0)
	v_mov_b32_e32 v12, v4
	v_mov_b32_e32 v13, v0
	v_mov_b32_e32 v14, v5
	v_mov_b32_e32 v15, v1
	v_pk_add_f32 v[12:13], v[12:13], v[14:15]
	v_mov_b32_e32 v14, v6
	v_mov_b32_e32 v15, v2
	v_pk_add_f32 v[12:13], v[14:15], v[12:13]
	v_mov_b32_e32 v14, v7
	v_mov_b32_e32 v15, v3
	v_pk_add_f32 v[12:13], v[14:15], v[12:13]
	v_mov_b32_e32 v14, v9
	v_add_f32_e32 v13, 0, v13
	v_add_f32_e32 v20, v12, v13
	v_mov_b32_e32 v12, v8
	v_mov_b32_e32 v13, v16
	v_mov_b32_e32 v15, v17
	v_pk_add_f32 v[12:13], v[12:13], v[14:15]
	v_mov_b32_e32 v14, v10
	v_mov_b32_e32 v15, v18
	v_pk_add_f32 v[12:13], v[14:15], v[12:13]
	v_mov_b32_e32 v14, v11
	v_mov_b32_e32 v15, v19
	v_pk_add_f32 v[12:13], v[14:15], v[12:13]
	s_nop 0
	v_add_f32_e32 v13, v13, v20
	v_add_f32_e32 v12, v12, v13
	v_mov_b32_e32 v240, v12
	v_mov_b32_e32 v13, v12
	s_nop 1
	v_permlane32_swap_b32_e32 v240, v13
	s_nop 1
	v_mov_b32_dpp v13, v240 quad_perm:[0,1,2,3] row_mask:0xc bank_mask:0xf
	s_waitcnt lgkmcnt(0)
	v_add_f32_e32 v12, v12, v13
	v_mov_b32_e32 v240, v12
	v_mov_b32_e32 v13, v12
	s_nop 1
	v_permlane16_swap_b32_e32 v240, v13
	s_nop 1
	v_mov_b32_dpp v13, v240 quad_perm:[0,1,2,3] row_mask:0xa bank_mask:0xf
	s_waitcnt lgkmcnt(0)
	v_add_f32_e32 v12, v12, v13
	s_nop 1
	v_mov_b32_dpp v13, v12 row_ror:8 row_mask:0xf bank_mask:0xf
	s_waitcnt lgkmcnt(0)
	v_add_f32_e32 v12, v12, v13
	s_nop 1
	v_mov_b32_dpp v13, v12 row_shl:4 row_mask:0xf bank_mask:0x5
	v_mov_b32_dpp v13, v12 row_shr:4 row_mask:0xf bank_mask:0xa
	s_waitcnt lgkmcnt(0)
	v_add_f32_e32 v12, v12, v13
	s_nop 1
	v_mov_b32_dpp v13, v12 quad_perm:[2,3,0,1] row_mask:0xf bank_mask:0xf
	s_waitcnt lgkmcnt(0)
	v_add_f32_e32 v12, v12, v13
	s_nop 1
	v_mov_b32_dpp v13, v12 quad_perm:[1,0,3,2] row_mask:0xf bank_mask:0xf
	s_waitcnt lgkmcnt(0)
	v_add_f32_e32 v22, v12, v13
	v_fmamk_f32 v12, v22, 0xba800000, v3
	v_fmamk_f32 v14, v22, 0xba800000, v2
	v_fmamk_f32 v2, v22, 0xba800000, v1
	v_fmamk_f32 v3, v22, 0xba800000, v5
	v_fmamk_f32 v20, v22, 0xba800000, v0
	v_fmamk_f32 v21, v22, 0xba800000, v4
	v_pk_mul_f32 v[0:1], v[2:3], v[2:3]
	v_fmamk_f32 v15, v22, 0xba800000, v6
	v_pk_fma_f32 v[0:1], v[20:21], v[20:21], v[0:1]
	v_fmamk_f32 v13, v22, 0xba800000, v7
	v_pk_fma_f32 v[0:1], v[14:15], v[14:15], v[0:1]
	v_fmamk_f32 v17, v22, 0xba800000, v17
	v_fmamk_f32 v4, v22, 0xba800000, v16
	v_fmamk_f32 v16, v22, 0xba800000, v9
	v_pk_fma_f32 v[24:25], v[12:13], v[12:13], v[0:1]
	v_fmamk_f32 v6, v22, 0xba800000, v11
	v_fmamk_f32 v0, v22, 0xba800000, v10
	v_fmac_f32_e32 v8, 0xba800000, v22
	v_mov_b32_e32 v9, v4
	v_pk_mul_f32 v[10:11], v[16:17], v[16:17]
	v_fmamk_f32 v1, v22, 0xba800000, v18
	v_pk_fma_f32 v[10:11], v[8:9], v[8:9], v[10:11]
	v_fmamk_f32 v7, v22, 0xba800000, v19
	v_pk_fma_f32 v[10:11], v[0:1], v[0:1], v[10:11]
	v_add_f32_e32 v5, v24, v25
	v_pk_fma_f32 v[10:11], v[6:7], v[6:7], v[10:11]
	s_nop 0
	v_add_f32_e32 v5, v11, v5
	v_add_f32_e32 v5, v10, v5
	v_mov_b32_e32 v240, v5
	v_mov_b32_e32 v9, v5
	s_nop 1
	v_permlane32_swap_b32_e32 v240, v9
	s_nop 1
	v_mov_b32_dpp v9, v240 quad_perm:[0,1,2,3] row_mask:0xc bank_mask:0xf
	s_waitcnt lgkmcnt(0)
	v_add_f32_e32 v5, v5, v9
	v_mov_b32_e32 v240, v5
	v_mov_b32_e32 v9, v5
	s_nop 1
	v_permlane16_swap_b32_e32 v240, v9
	s_nop 1
	v_mov_b32_dpp v9, v240 quad_perm:[0,1,2,3] row_mask:0xa bank_mask:0xf
	s_waitcnt lgkmcnt(0)
	v_add_f32_e32 v5, v5, v9
	s_nop 1
	v_mov_b32_dpp v9, v5 row_ror:8 row_mask:0xf bank_mask:0xf
	s_waitcnt lgkmcnt(0)
	v_add_f32_e32 v5, v5, v9
	s_nop 1
	v_mov_b32_dpp v9, v5 row_shl:4 row_mask:0xf bank_mask:0x5
	v_mov_b32_dpp v9, v5 row_shr:4 row_mask:0xf bank_mask:0xa
	s_waitcnt lgkmcnt(0)
	v_add_f32_e32 v5, v5, v9
	s_nop 1
	v_mov_b32_dpp v9, v5 quad_perm:[2,3,0,1] row_mask:0xf bank_mask:0xf
	s_waitcnt lgkmcnt(0)
	v_add_f32_e32 v5, v5, v9
	s_nop 1
	v_mov_b32_dpp v9, v5 quad_perm:[1,0,3,2] row_mask:0xf bank_mask:0xf
	s_waitcnt lgkmcnt(0)
	v_add_f32_e32 v5, v5, v9
	v_fmamk_f32 v5, v5, 0x3a800000, v250
	v_mul_f32_e32 v9, 0x4b800000, v5
	v_cmp_gt_f32_e32 vcc, s81, v5
	s_nop 1
	v_cndmask_b32_e32 v5, v5, v9, vcc
	v_rsq_f32_e32 v5, v5
	s_nop 0
	v_mul_f32_e32 v9, 0x45800000, v5
	v_cndmask_b32_e32 v10, v5, v9, vcc
	s_and_saveexec_b64 s[2:3], s[0:1]
	s_cbranch_execz .LBB0_505
	v_ashrrev_i32_e32 v71, 31, v70
	v_readlane_b32 s4, v254, 29
	v_lshlrev_b64 v[18:19], 2, v[70:71]
	v_readlane_b32 s5, v254, 30
	v_mul_f32_e32 v5, 0x3a800000, v22
	s_nop 0
	v_lshl_add_u64 v[22:23], s[4:5], 0, v[18:19]
	v_lshl_add_u64 v[18:19], s[78:79], 0, v[18:19]
	v_add_co_u32_e32 v18, vcc, 0xdf000, v18
	global_store_dword v[22:23], v5, off
	s_nop 0
	v_addc_co_u32_e32 v19, vcc, 0, v19, vcc
	global_store_dword v[18:19], v10, off offset:4
	s_branch .LBB0_505

; DI float shx(float v, int m, int lane) { return __builtin_bit_cast(float, __builtin_amdgcn_ds_bpermute((lane ^ m) << 2, __builtin_bit_cast(int, v))); }
; template <int PR>
; DI void prep_rows(const int lane, const Params& p, int l, int which, int rbeg, int rend, int gw, int nw) {
;     ...
;             for (int rr = 0; rr < PR; ++rr) { float s = 0.f;
; #pragma unroll
;                 for (int i = 0; i < 4; ++i) s += v[rr][i][0] + v[rr][i][1] + v[rr][i][2] + v[rr][i][3];
;                 sm[rr] = s; }
; #pragma unroll
;             for (int o = 32; o >= 1; o >>= 1)
; #pragma unroll
;                 for (int rr = 0; rr < PR; ++rr) sm[rr] += shx(sm[rr], o, lane);
.LBB0_537:
	s_waitcnt vmcnt(0)
	v_mov_b32_e32 v82, v12
	v_mov_b32_e32 v83, v8
	v_mov_b32_e32 v84, v13
	v_mov_b32_e32 v85, v9
	v_pk_add_f32 v[82:83], v[82:83], v[84:85]
	v_mov_b32_e32 v84, v14
	v_mov_b32_e32 v85, v10
	v_pk_add_f32 v[82:83], v[82:83], v[84:85]
	v_mov_b32_e32 v84, v15
	v_mov_b32_e32 v85, v11
	v_pk_add_f32 v[82:83], v[82:83], v[84:85]
	v_mov_b32_e32 v84, v5
	v_add_f32_e32 v65, 0, v83
	v_add_f32_e32 v65, v82, v65
	v_mov_b32_e32 v82, v4
	v_mov_b32_e32 v83, v0
	v_mov_b32_e32 v85, v1
	v_pk_add_f32 v[82:83], v[82:83], v[84:85]
	v_mov_b32_e32 v84, v6
	v_mov_b32_e32 v85, v2
	v_pk_add_f32 v[82:83], v[82:83], v[84:85]
	v_mov_b32_e32 v84, v7
	v_mov_b32_e32 v85, v3
	v_pk_add_f32 v[82:83], v[82:83], v[84:85]
	v_mov_b32_e32 v84, v33
	v_add_f32_e32 v65, v83, v65
	v_add_f32_e32 v65, v82, v65
	v_mov_b32_e32 v82, v32
	v_mov_b32_e32 v83, v28
	v_mov_b32_e32 v85, v29
	v_pk_add_f32 v[82:83], v[82:83], v[84:85]
	v_mov_b32_e32 v84, v34
	v_mov_b32_e32 v85, v30
	v_pk_add_f32 v[82:83], v[82:83], v[84:85]
	v_mov_b32_e32 v84, v35
	v_mov_b32_e32 v85, v31
	v_pk_add_f32 v[82:83], v[82:83], v[84:85]
	v_mov_b32_e32 v84, v17
	v_add_f32_e32 v75, 0, v83
	v_add_f32_e32 v75, v82, v75
	v_mov_b32_e32 v82, v16
	v_mov_b32_e32 v83, v20
	v_mov_b32_e32 v85, v21
	v_pk_add_f32 v[82:83], v[82:83], v[84:85]
	v_mov_b32_e32 v84, v18
	v_mov_b32_e32 v85, v22
	v_pk_add_f32 v[82:83], v[82:83], v[84:85]
	v_mov_b32_e32 v84, v19
	v_mov_b32_e32 v85, v23
	v_pk_add_f32 v[82:83], v[82:83], v[84:85]
	v_mov_b32_e32 v84, v49
	v_add_f32_e32 v75, v83, v75
	v_add_f32_e32 v75, v82, v75
	v_mov_b32_e32 v82, v48
	v_mov_b32_e32 v83, v44
	v_mov_b32_e32 v85, v45
	v_pk_add_f32 v[82:83], v[82:83], v[84:85]
	v_mov_b32_e32 v84, v50
	v_mov_b32_e32 v85, v46
	v_pk_add_f32 v[82:83], v[82:83], v[84:85]
	v_mov_b32_e32 v84, v51
	v_mov_b32_e32 v85, v47
	v_pk_add_f32 v[82:83], v[82:83], v[84:85]
	v_mov_b32_e32 v84, v25
	v_add_f32_e32 v81, 0, v83
	v_add_f32_e32 v81, v82, v81
	v_mov_b32_e32 v82, v24
	v_mov_b32_e32 v83, v36
	v_mov_b32_e32 v85, v37
	v_pk_add_f32 v[82:83], v[82:83], v[84:85]
	v_mov_b32_e32 v84, v26
	v_mov_b32_e32 v85, v38
	v_pk_add_f32 v[82:83], v[82:83], v[84:85]
	v_mov_b32_e32 v84, v27
	v_mov_b32_e32 v85, v39
	v_pk_add_f32 v[82:83], v[82:83], v[84:85]
	v_mov_b32_e32 v84, v61
	v_add_f32_e32 v81, v83, v81
	v_add_f32_e32 v81, v82, v81
	v_mov_b32_e32 v82, v60
	v_mov_b32_e32 v83, v56
	v_mov_b32_e32 v85, v57
	v_pk_add_f32 v[82:83], v[82:83], v[84:85]
	v_mov_b32_e32 v84, v62
	v_mov_b32_e32 v85, v58
	v_pk_add_f32 v[82:83], v[82:83], v[84:85]
	v_mov_b32_e32 v84, v63
	v_mov_b32_e32 v85, v59
	v_pk_add_f32 v[82:83], v[82:83], v[84:85]
	v_mov_b32_e32 v84, v41
	v_add_f32_e32 v83, 0, v83
	v_add_f32_e32 v86, v82, v83
	v_mov_b32_e32 v82, v40
	v_mov_b32_e32 v83, v52
	v_mov_b32_e32 v85, v53
	v_pk_add_f32 v[82:83], v[82:83], v[84:85]
	v_mov_b32_e32 v84, v42
	v_mov_b32_e32 v85, v54
	v_pk_add_f32 v[82:83], v[82:83], v[84:85]
	v_mov_b32_e32 v84, v43
	v_mov_b32_e32 v85, v55
	v_pk_add_f32 v[82:83], v[82:83], v[84:85]
	v_mov_b32_e32 v240, v75
	v_mov_b32_e32 v84, v75
	s_nop 1
	v_permlane32_swap_b32_e32 v240, v84
	s_nop 1
	v_mov_b32_dpp v84, v240 quad_perm:[0,1,2,3] row_mask:0xc bank_mask:0xf
	v_add_f32_e32 v83, v83, v86
	v_add_f32_e32 v82, v82, v83
	v_mov_b32_e32 v240, v65
	v_mov_b32_e32 v83, v65
	s_nop 1
	v_permlane32_swap_b32_e32 v240, v83
	s_nop 1
	v_mov_b32_dpp v83, v240 quad_perm:[0,1,2,3] row_mask:0xc bank_mask:0xf
	v_mov_b32_e32 v240, v82
	v_mov_b32_e32 v86, v82
	s_nop 1
	v_permlane32_swap_b32_e32 v240, v86
	s_nop 1
	v_mov_b32_dpp v86, v240 quad_perm:[0,1,2,3] row_mask:0xc bank_mask:0xf
	v_mov_b32_e32 v240, v81
	v_mov_b32_e32 v85, v81
	s_nop 1
	v_permlane32_swap_b32_e32 v240, v85
	s_nop 1
	v_mov_b32_dpp v85, v240 quad_perm:[0,1,2,3] row_mask:0xc bank_mask:0xf
	s_waitcnt lgkmcnt(0)
	v_add_f32_e32 v75, v75, v84
	v_mov_b32_e32 v240, v75
	v_mov_b32_e32 v84, v75
	s_nop 1
	v_permlane16_swap_b32_e32 v240, v84
	s_nop 1
	v_mov_b32_dpp v84, v240 quad_perm:[0,1,2,3] row_mask:0xa bank_mask:0xf
	v_add_f32_e32 v65, v65, v83
	v_add_f32_e32 v82, v82, v86
	v_mov_b32_e32 v240, v65
	v_mov_b32_e32 v83, v65
	s_nop 1
	v_permlane16_swap_b32_e32 v240, v83
	s_nop 1
	v_mov_b32_dpp v83, v240 quad_perm:[0,1,2,3] row_mask:0xa bank_mask:0xf
	v_mov_b32_e32 v240, v82
	v_mov_b32_e32 v86, v82
	s_nop 1
	v_permlane16_swap_b32_e32 v240, v86
	s_nop 1
	v_mov_b32_dpp v86, v240 quad_perm:[0,1,2,3] row_mask:0xa bank_mask:0xf
	v_add_f32_e32 v81, v81, v85
	v_mov_b32_e32 v240, v81
	v_mov_b32_e32 v85, v81
	s_nop 1
	v_permlane16_swap_b32_e32 v240, v85
	s_nop 1
	v_mov_b32_dpp v85, v240 quad_perm:[0,1,2,3] row_mask:0xa bank_mask:0xf
	s_waitcnt lgkmcnt(3)
	v_add_f32_e32 v75, v75, v84
	s_waitcnt lgkmcnt(2)
	v_add_f32_e32 v65, v65, v83
	s_waitcnt lgkmcnt(1)
	v_add_f32_e32 v82, v82, v86
	s_nop 1
	v_mov_b32_dpp v83, v65 row_ror:8 row_mask:0xf bank_mask:0xf
	s_nop 1
	v_mov_b32_dpp v86, v82 row_ror:8 row_mask:0xf bank_mask:0xf
	s_waitcnt lgkmcnt(2)
	v_add_f32_e32 v81, v81, v85
	s_nop 1
	v_mov_b32_dpp v84, v75 row_ror:8 row_mask:0xf bank_mask:0xf
	s_nop 1
	v_mov_b32_dpp v85, v81 row_ror:8 row_mask:0xf bank_mask:0xf
	s_waitcnt lgkmcnt(3)
	v_add_f32_e32 v65, v65, v83
	s_waitcnt lgkmcnt(2)
	v_add_f32_e32 v82, v82, v86
	s_nop 1
	v_mov_b32_dpp v83, v65 row_shl:4 row_mask:0xf bank_mask:0x5
	v_mov_b32_dpp v83, v65 row_shr:4 row_mask:0xf bank_mask:0xa
	s_waitcnt lgkmcnt(2)
	v_add_f32_e32 v75, v75, v84
	s_nop 1
	v_mov_b32_dpp v86, v82 row_shl:4 row_mask:0xf bank_mask:0x5
	v_mov_b32_dpp v86, v82 row_shr:4 row_mask:0xf bank_mask:0xa
	s_waitcnt lgkmcnt(2)
; DI float shx(float v, int m, int lane) { return __builtin_bit_cast(float, __builtin_amdgcn_ds_bpermute((lane ^ m) << 2, __builtin_bit_cast(int, v))); }
; template <int PR>
; DI void prep_rows(const int lane, const Params& p, int l, int which, int rbeg, int rend, int gw, int nw) {
;     ...
;             for (int o = 32; o >= 1; o >>= 1)
; #pragma unroll
;                 for (int rr = 0; rr < PR; ++rr) sm[rr] += shx(sm[rr], o, lane);
; #pragma unroll
;             for (int rr = 0; rr < PR; ++rr) { const float mean = sm[rr] * (1.f / 1024.f); sm[rr] = mean; float q = 0.f;
; #pragma unroll
;                 for (int i = 0; i < 4; ++i) { v[rr][i] -= mean; q += v[rr][i][0] * v[rr][i][0] + v[rr][i][1] * v[rr][i][1] + v[rr][i][2] * v[rr][i][2] + v[rr][i][3] * v[rr][i][3]; }
;                 sq[rr] = q; }
; #pragma unroll
;             for (int o = 32; o >= 1; o >>= 1)
; #pragma unroll
;                 for (int rr = 0; rr < PR; ++rr) sq[rr] += shx(sq[rr], o, lane);
	v_add_f32_e32 v81, v81, v85
	s_nop 1
	v_mov_b32_dpp v84, v75 row_shl:4 row_mask:0xf bank_mask:0x5
	v_mov_b32_dpp v84, v75 row_shr:4 row_mask:0xf bank_mask:0xa
	s_nop 1
	v_mov_b32_dpp v85, v81 row_shl:4 row_mask:0xf bank_mask:0x5
	v_mov_b32_dpp v85, v81 row_shr:4 row_mask:0xf bank_mask:0xa
	s_waitcnt lgkmcnt(3)
	v_add_f32_e32 v65, v65, v83
	s_waitcnt lgkmcnt(2)
	v_add_f32_e32 v82, v82, v86
	s_nop 1
	v_mov_b32_dpp v83, v65 quad_perm:[2,3,0,1] row_mask:0xf bank_mask:0xf
	s_waitcnt lgkmcnt(2)
	v_add_f32_e32 v75, v75, v84
	s_nop 1
	v_mov_b32_dpp v86, v82 quad_perm:[2,3,0,1] row_mask:0xf bank_mask:0xf
	s_waitcnt lgkmcnt(2)
	v_add_f32_e32 v81, v81, v85
	s_nop 1
	v_mov_b32_dpp v84, v75 quad_perm:[2,3,0,1] row_mask:0xf bank_mask:0xf
	s_nop 1
	v_mov_b32_dpp v85, v81 quad_perm:[2,3,0,1] row_mask:0xf bank_mask:0xf
	s_waitcnt lgkmcnt(3)
	v_add_f32_e32 v65, v65, v83
	s_waitcnt lgkmcnt(2)
	v_add_f32_e32 v82, v82, v86
	s_nop 1
	v_mov_b32_dpp v83, v65 quad_perm:[1,0,3,2] row_mask:0xf bank_mask:0xf
	s_waitcnt lgkmcnt(2)
	v_add_f32_e32 v75, v75, v84
	s_nop 1
	v_mov_b32_dpp v86, v82 quad_perm:[1,0,3,2] row_mask:0xf bank_mask:0xf
	s_waitcnt lgkmcnt(2)
	v_add_f32_e32 v81, v81, v85
	s_nop 1
	v_mov_b32_dpp v84, v75 quad_perm:[1,0,3,2] row_mask:0xf bank_mask:0xf
	s_nop 1
	v_mov_b32_dpp v85, v81 quad_perm:[1,0,3,2] row_mask:0xf bank_mask:0xf
	s_waitcnt lgkmcnt(3)
	v_add_f32_e32 v88, v65, v83
	s_waitcnt lgkmcnt(2)
	v_add_f32_e32 v65, v82, v86
	v_fmamk_f32 v86, v88, 0xba800000, v9
	v_fmamk_f32 v87, v88, 0xba800000, v13
	v_fmac_f32_e32 v12, 0xba800000, v88
	s_waitcnt lgkmcnt(1)
	v_add_f32_e32 v90, v75, v84
	v_fmamk_f32 v82, v88, 0xba800000, v11
	v_fmamk_f32 v84, v88, 0xba800000, v10
	v_fmac_f32_e32 v8, 0xba800000, v88
	v_mov_b32_e32 v9, v12
	v_pk_mul_f32 v[10:11], v[86:87], v[86:87]
	s_waitcnt lgkmcnt(0)
	v_add_f32_e32 v81, v81, v85
	v_fmamk_f32 v85, v88, 0xba800000, v14
	v_pk_fma_f32 v[10:11], v[8:9], v[8:9], v[10:11]
	v_fmamk_f32 v83, v88, 0xba800000, v15
	v_pk_fma_f32 v[10:11], v[84:85], v[84:85], v[10:11]
	v_fmamk_f32 v15, v88, 0xba800000, v1
	v_fmac_f32_e32 v0, 0xba800000, v88
	v_fmamk_f32 v14, v88, 0xba800000, v5
	v_pk_fma_f32 v[96:97], v[82:83], v[82:83], v[10:11]
	v_fmamk_f32 v11, v88, 0xba800000, v3
	v_fmamk_f32 v3, v88, 0xba800000, v2
	v_fmamk_f32 v10, v88, 0xba800000, v7
	v_fmamk_f32 v2, v88, 0xba800000, v6
	v_fmac_f32_e32 v4, 0xba800000, v88
	v_mov_b32_e32 v5, v0
	v_pk_mul_f32 v[6:7], v[14:15], v[14:15]
	v_add_f32_e32 v1, v96, v97
	v_pk_fma_f32 v[6:7], v[4:5], v[4:5], v[6:7]
	v_fmamk_f32 v29, v90, 0xba800000, v29
	v_pk_fma_f32 v[6:7], v[2:3], v[2:3], v[6:7]
	v_fmamk_f32 v33, v90, 0xba800000, v33
	v_pk_fma_f32 v[6:7], v[10:11], v[10:11], v[6:7]
	v_fmac_f32_e32 v28, 0xba800000, v90
	v_add_f32_e32 v1, v7, v1
	v_add_f32_e32 v1, v6, v1
	v_mul_f32_e32 v5, v29, v29
	v_fmac_f32_e32 v32, 0xba800000, v90
	v_mul_f32_e32 v6, v33, v33
	v_fmamk_f32 v30, v90, 0xba800000, v30
	v_fmac_f32_e32 v5, v28, v28
	v_fmamk_f32 v34, v90, 0xba800000, v34
	v_fmac_f32_e32 v6, v32, v32
	v_fmamk_f32 v31, v90, 0xba800000, v31
	v_fmac_f32_e32 v5, v30, v30
	v_fmamk_f32 v35, v90, 0xba800000, v35
	v_fmac_f32_e32 v6, v34, v34
	v_fmac_f32_e32 v5, v31, v31
	v_fmac_f32_e32 v6, v35, v35
	v_fmamk_f32 v21, v90, 0xba800000, v21
	v_add_f32_e32 v5, v5, v6
	v_fmac_f32_e32 v20, 0xba800000, v90
	v_mul_f32_e32 v6, v21, v21
	v_fmamk_f32 v22, v90, 0xba800000, v22
	v_fmac_f32_e32 v6, v20, v20
	v_fmamk_f32 v23, v90, 0xba800000, v23
	v_fmac_f32_e32 v6, v22, v22
	v_fmamk_f32 v17, v90, 0xba800000, v17
	v_fmac_f32_e32 v6, v23, v23
	v_fmac_f32_e32 v16, 0xba800000, v90
	v_mul_f32_e32 v9, v17, v17
	v_add_f32_e32 v5, v6, v5
	v_fmamk_f32 v6, v90, 0xba800000, v18
	v_fmac_f32_e32 v9, v16, v16
	v_fmamk_f32 v7, v90, 0xba800000, v19
	v_fmac_f32_e32 v9, v6, v6
	v_fmac_f32_e32 v9, v7, v7
	v_fmamk_f32 v45, v81, 0xba800000, v45
	v_fmamk_f32 v49, v81, 0xba800000, v49
	v_add_f32_e32 v5, v9, v5
	v_fmac_f32_e32 v44, 0xba800000, v81
	v_mul_f32_e32 v9, v45, v45
	v_fmac_f32_e32 v48, 0xba800000, v81
	v_mul_f32_e32 v13, v49, v49
	v_fmamk_f32 v46, v81, 0xba800000, v46
	v_fmac_f32_e32 v9, v44, v44
	v_fmamk_f32 v50, v81, 0xba800000, v50
	v_fmac_f32_e32 v13, v48, v48
	v_fmamk_f32 v47, v81, 0xba800000, v47
	v_fmac_f32_e32 v9, v46, v46
	v_fmamk_f32 v51, v81, 0xba800000, v51
	v_fmac_f32_e32 v13, v50, v50
	v_fmac_f32_e32 v9, v47, v47
	v_fmac_f32_e32 v13, v51, v51
	v_fmamk_f32 v37, v81, 0xba800000, v37
	v_add_f32_e32 v9, v9, v13
	v_fmac_f32_e32 v36, 0xba800000, v81
	v_mul_f32_e32 v13, v37, v37
	v_fmamk_f32 v38, v81, 0xba800000, v38
	v_fmac_f32_e32 v13, v36, v36
	v_fmamk_f32 v39, v81, 0xba800000, v39
	v_fmac_f32_e32 v13, v38, v38
	v_fmac_f32_e32 v13, v39, v39
	v_fmamk_f32 v25, v81, 0xba800000, v25
	v_add_f32_e32 v9, v13, v9
	v_fmac_f32_e32 v24, 0xba800000, v81
	v_mul_f32_e32 v13, v25, v25
	v_fmamk_f32 v18, v81, 0xba800000, v26
	v_fmac_f32_e32 v13, v24, v24
	v_fmamk_f32 v19, v81, 0xba800000, v27
	v_fmac_f32_e32 v13, v18, v18
	v_fmac_f32_e32 v13, v19, v19
	v_fmamk_f32 v57, v65, 0xba800000, v57
	v_fmamk_f32 v61, v65, 0xba800000, v61
	v_add_f32_e32 v9, v13, v9
	v_fmac_f32_e32 v56, 0xba800000, v65
	v_mul_f32_e32 v13, v57, v57
	v_fmac_f32_e32 v60, 0xba800000, v65
	v_mul_f32_e32 v26, v61, v61
	v_fmamk_f32 v58, v65, 0xba800000, v58
	v_fmac_f32_e32 v13, v56, v56
	v_fmamk_f32 v62, v65, 0xba800000, v62
	v_fmac_f32_e32 v26, v60, v60
	v_fmamk_f32 v59, v65, 0xba800000, v59
	v_fmac_f32_e32 v13, v58, v58
	v_fmamk_f32 v63, v65, 0xba800000, v63
	v_fmac_f32_e32 v26, v62, v62
	v_fmac_f32_e32 v13, v59, v59
	v_fmac_f32_e32 v26, v63, v63
	v_fmamk_f32 v53, v65, 0xba800000, v53
	v_add_f32_e32 v13, v13, v26
	v_fmac_f32_e32 v52, 0xba800000, v65
	v_mul_f32_e32 v26, v53, v53
	v_fmamk_f32 v54, v65, 0xba800000, v54
	v_fmac_f32_e32 v26, v52, v52
	v_fmamk_f32 v55, v65, 0xba800000, v55
	v_fmac_f32_e32 v26, v54, v54
	v_fmamk_f32 v27, v65, 0xba800000, v43
	v_mov_b32_e32 v240, v1
	v_mov_b32_e32 v43, v1
	s_nop 1
	v_permlane32_swap_b32_e32 v240, v43
	s_nop 1
	v_mov_b32_dpp v43, v240 quad_perm:[0,1,2,3] row_mask:0xc bank_mask:0xf
	v_fmac_f32_e32 v26, v55, v55
	v_fmamk_f32 v41, v65, 0xba800000, v41
	v_add_f32_e32 v13, v26, v13
	v_fmamk_f32 v26, v65, 0xba800000, v42
	v_fmac_f32_e32 v40, 0xba800000, v65
	v_mul_f32_e32 v42, v41, v41
	v_fmac_f32_e32 v42, v40, v40
	v_fmac_f32_e32 v42, v26, v26
	v_fmac_f32_e32 v42, v27, v27
	s_waitcnt lgkmcnt(0)
; DI float shx(float v, int m, int lane) { return __builtin_bit_cast(float, __builtin_amdgcn_ds_bpermute((lane ^ m) << 2, __builtin_bit_cast(int, v))); }
; template <int PR>
; DI void prep_rows(const int lane, const Params& p, int l, int which, int rbeg, int rend, int gw, int nw) {
;     ...
;             for (int o = 32; o >= 1; o >>= 1)
; #pragma unroll
;                 for (int rr = 0; rr < PR; ++rr) sq[rr] += shx(sq[rr], o, lane);
; #pragma unroll
;             for (int rr = 0; rr < PR; ++rr) { sq[rr] = rsqrtf(sq[rr] * (1.f / 1024.f) + LN_EPS);
;                 if (which != 2 && lane == 0) { P_WSF(OFF_STATS)[2 * (row + rr)] = sm[rr]; P_WSF(OFF_STATS)[2 * (row + rr) + 1] = sq[rr]; } }
	v_add_f32_e32 v1, v1, v43
	v_add_f32_e32 v13, v42, v13
	v_mov_b32_e32 v240, v5
	v_mov_b32_e32 v42, v5
	s_nop 1
	v_permlane32_swap_b32_e32 v240, v42
	s_nop 1
	v_mov_b32_dpp v42, v240 quad_perm:[0,1,2,3] row_mask:0xc bank_mask:0xf
	v_mov_b32_e32 v240, v1
	v_mov_b32_e32 v92, v1
	s_nop 1
	v_permlane16_swap_b32_e32 v240, v92
	s_nop 1
	v_mov_b32_dpp v92, v240 quad_perm:[0,1,2,3] row_mask:0xa bank_mask:0xf
	v_mov_b32_e32 v240, v13
	v_mov_b32_e32 v75, v13
	s_nop 1
	v_permlane32_swap_b32_e32 v240, v75
	s_nop 1
	v_mov_b32_dpp v75, v240 quad_perm:[0,1,2,3] row_mask:0xc bank_mask:0xf
	v_mov_b32_e32 v240, v9
	v_mov_b32_e32 v43, v9
	s_nop 1
	v_permlane32_swap_b32_e32 v240, v43
	s_nop 1
	v_mov_b32_dpp v43, v240 quad_perm:[0,1,2,3] row_mask:0xc bank_mask:0xf
	s_waitcnt lgkmcnt(3)
	v_add_f32_e32 v5, v5, v42
	s_waitcnt lgkmcnt(2)
	v_add_f32_e32 v1, v1, v92
	v_mov_b32_e32 v240, v5
	v_mov_b32_e32 v42, v5
	s_nop 1
	v_permlane16_swap_b32_e32 v240, v42
	s_nop 1
	v_mov_b32_dpp v42, v240 quad_perm:[0,1,2,3] row_mask:0xa bank_mask:0xf
	s_nop 1
	v_mov_b32_dpp v92, v1 row_ror:8 row_mask:0xf bank_mask:0xf
	s_waitcnt lgkmcnt(3)
	v_add_f32_e32 v13, v13, v75
	v_mov_b32_e32 v240, v13
	v_mov_b32_e32 v75, v13
	s_nop 1
	v_permlane16_swap_b32_e32 v240, v75
	s_nop 1
	v_mov_b32_dpp v75, v240 quad_perm:[0,1,2,3] row_mask:0xa bank_mask:0xf
	s_waitcnt lgkmcnt(3)
	v_add_f32_e32 v9, v9, v43
	v_mov_b32_e32 v240, v9
	v_mov_b32_e32 v43, v9
	s_nop 1
	v_permlane16_swap_b32_e32 v240, v43
	s_nop 1
	v_mov_b32_dpp v43, v240 quad_perm:[0,1,2,3] row_mask:0xa bank_mask:0xf
	s_waitcnt lgkmcnt(3)
	v_add_f32_e32 v5, v5, v42
	s_waitcnt lgkmcnt(2)
	v_add_f32_e32 v1, v1, v92
	s_nop 1
	v_mov_b32_dpp v42, v5 row_ror:8 row_mask:0xf bank_mask:0xf
	s_nop 1
	v_mov_b32_dpp v92, v1 row_shl:4 row_mask:0xf bank_mask:0x5
	v_mov_b32_dpp v92, v1 row_shr:4 row_mask:0xf bank_mask:0xa
	s_waitcnt lgkmcnt(3)
	v_add_f32_e32 v13, v13, v75
	s_nop 1
	v_mov_b32_dpp v75, v13 row_ror:8 row_mask:0xf bank_mask:0xf
	s_waitcnt lgkmcnt(3)
	v_add_f32_e32 v9, v9, v43
	s_nop 1
	v_mov_b32_dpp v43, v9 row_ror:8 row_mask:0xf bank_mask:0xf
	s_waitcnt lgkmcnt(3)
	v_add_f32_e32 v5, v5, v42
	s_waitcnt lgkmcnt(2)
	v_add_f32_e32 v1, v1, v92
	s_nop 1
	v_mov_b32_dpp v42, v5 row_shl:4 row_mask:0xf bank_mask:0x5
	v_mov_b32_dpp v42, v5 row_shr:4 row_mask:0xf bank_mask:0xa
	s_nop 1
	v_mov_b32_dpp v92, v1 quad_perm:[2,3,0,1] row_mask:0xf bank_mask:0xf
	s_waitcnt lgkmcnt(3)
	v_add_f32_e32 v13, v13, v75
	s_nop 1
	v_mov_b32_dpp v75, v13 row_shl:4 row_mask:0xf bank_mask:0x5
	v_mov_b32_dpp v75, v13 row_shr:4 row_mask:0xf bank_mask:0xa
	s_waitcnt lgkmcnt(3)
	v_add_f32_e32 v9, v9, v43
	s_nop 1
	v_mov_b32_dpp v43, v9 row_shl:4 row_mask:0xf bank_mask:0x5
	v_mov_b32_dpp v43, v9 row_shr:4 row_mask:0xf bank_mask:0xa
	s_waitcnt lgkmcnt(3)
	v_add_f32_e32 v5, v5, v42
	s_waitcnt lgkmcnt(2)
	v_add_f32_e32 v42, v1, v92
	s_nop 1
	v_mov_b32_dpp v1, v5 quad_perm:[2,3,0,1] row_mask:0xf bank_mask:0xf
	s_nop 1
	v_mov_b32_dpp v96, v42 quad_perm:[1,0,3,2] row_mask:0xf bank_mask:0xf
	s_waitcnt lgkmcnt(3)
	v_add_f32_e32 v13, v13, v75
	s_nop 1
	v_mov_b32_dpp v92, v13 quad_perm:[2,3,0,1] row_mask:0xf bank_mask:0xf
	s_waitcnt lgkmcnt(3)
	v_add_f32_e32 v9, v9, v43
	s_nop 1
	v_mov_b32_dpp v75, v9 quad_perm:[2,3,0,1] row_mask:0xf bank_mask:0xf
	s_waitcnt lgkmcnt(3)
	v_add_f32_e32 v43, v5, v1
	s_waitcnt lgkmcnt(2)
	v_add_f32_e32 v5, v42, v96
	v_fmamk_f32 v5, v5, 0x3a800000, v250
	s_waitcnt lgkmcnt(1)
	v_add_f32_e32 v1, v13, v92
	v_mul_f32_e32 v13, 0x4b800000, v5
	v_cmp_gt_f32_e32 vcc, s81, v5
	s_waitcnt lgkmcnt(0)
	v_add_f32_e32 v9, v9, v75
	s_nop 1
	v_mov_b32_dpp v92, v43 quad_perm:[1,0,3,2] row_mask:0xf bank_mask:0xf
	v_cndmask_b32_e32 v5, v5, v13, vcc
	v_rsq_f32_e32 v42, v5
	s_nop 1
	v_mov_b32_dpp v13, v9 quad_perm:[1,0,3,2] row_mask:0xf bank_mask:0xf
	s_nop 1
	v_mov_b32_dpp v5, v1 quad_perm:[1,0,3,2] row_mask:0xf bank_mask:0xf
	v_mul_f32_e32 v75, 0x45800000, v42
	v_cndmask_b32_e32 v42, v42, v75, vcc
	v_ashrrev_i32_e32 v75, 31, v74
	s_and_saveexec_b64 s[2:3], s[0:1]
	s_cbranch_execz .LBB0_539
	v_readlane_b32 s10, v254, 29
	v_lshlrev_b64 v[96:97], 2, v[74:75]
	v_readlane_b32 s11, v254, 30
	v_mul_f32_e32 v88, 0x3a800000, v88
	v_lshl_add_u64 v[98:99], s[78:79], 0, v[96:97]
	v_lshl_add_u64 v[96:97], s[10:11], 0, v[96:97]
	global_store_dword v[96:97], v88, off
	v_add_co_u32_e32 v96, vcc, 0xdf000, v98
	s_nop 1
	v_addc_co_u32_e32 v97, vcc, 0, v99, vcc
	global_store_dword v[96:97], v42, off offset:4
